# attention: second unit of each (batch, head) pair starts its K/V ring at slot 2 with tile 0 staged during the first unit's epilogue; loop entry keeps tile 1 in flight
# speedup vs baseline: 1.0187x; 1.0010x over previous
; template <bool FIXED> __device__ __forceinline__ void attn_unit(int b, int h, int qb, const bf16* __restrict__ P, bf16* __restrict__ MIX, const float* __restrict__ BT, const float* __restrict__ subg, ...
;     ...
;   DMA_TILE(0, 0); DMA_TILE(1, 1);
; __global__ void __launch_bounds__(NWAVES * 64, 2) hybrid_fwd(Args args) {
;     ...
;                 {   const int qb = half == 0 ? 15 - s : s, hh = bh % NH;
;                     float bm = fmaxf(fmaxf(BT[hh * 768 + 128 + lane], BT[hh * 768 + 128 + 64 + lane]), fmaxf(BT[hh * 768 + 384 + 128 + lane], BT[hh * 768 + 384 + 128 + 64 + lane]));
; #pragma unroll
;                     for (int o = 1; o < 64; o <<= 1) bm = fmaxf(bm, __shfl_xor(bm, o));
;                     const float sref = 11.8f * gqk + bm + 0.25f;
;                     if (sref <= 40.f) att::attn_unit<true>(bh / NH, hh, qb, (const att::bf16*)PROJ, (att::bf16*)MIX, BT, args.in[z + 10] + ll * 128, lam, 1.0f - lam_init, sref, args.in[z + 3] + (size_t)ll * 3 * CONVW, pr * 8 + half * 4, (char*)lds);
.LBB0_301:
	global_load_dword v0, v[132:133], off
	global_load_dword v1, v[130:131], off
	global_load_dword v2, v[128:129], off offset:512
	global_load_dword v3, v[128:129], off offset:768
	s_and_b64 s[0:1], s[30:31], exec
	s_cselect_b32 s73, s66, s3
	v_lshlrev_b32_e32 v100, 2, v169
	v_readfirstlane_b32 s8, v169
	global_load_dword v102, v100, s[10:11]
	global_load_dword v103, v100, s[10:11] offset:2048
	s_ashr_i32 s8, s8, 8
	s_mul_i32 s8, s8, 0x600
	s_add_u32 s8, s10, s8
	s_addc_u32 s9, s11, 0
	global_load_dword v104, v145, s[8:9] offset:1020
	s_mov_b32 s0, 0x42200000
	s_or_b32 s71, s6, s67
	s_lshl_b32 s34, s73, 7
	v_mov_b32_e32 v80, v169
	v_readfirstlane_b32 s25, v169
	s_nop 1
	s_ashr_i32 s1, s25, 6
	s_ashr_i32 s26, s25, 8
	s_and_b32 s24, s1, 3
	s_lshl_b32 s99, s24, 5
	s_or_b32 s99, s99, s34
	v_and_b32_e32 v134, 31, v80
	s_or_b32 s22, s54, s99
	v_bfe_u32 v167, v80, 5, 1
	v_lshlrev_b32_e32 v144, 4, v167
	s_lshl_b32 s8, s1, 3
	v_bfe_u32 v93, v80, 2, 2
	v_and_b32_e32 v168, 63, v80
	v_lshlrev_b32_e32 v166, 3, v168
	v_bfe_u32 v92, v80, 4, 2
	v_and_b32_e32 v95, 32, v80
	v_and_b32_e32 v96, 24, v166
	v_lshlrev_b32_e32 v99, 4, v80
	v_mov_b32_e32 v89, v145
	v_mov_b32_e32 v85, v145
	v_mov_b32_e32 v87, v145
	v_or_b32_e32 v81, s22, v134
	v_mov_b64_e32 v[82:83], s[16:17]
	v_mad_u64_u32 v[82:83], s[6:7], v81, s70, v[82:83]
	s_lshl_b32 s6, s26, 6
	v_mad_i32_i24 v83, s55, v196, v83
	s_ashr_i32 s7, s6, 31
	v_lshl_add_u64 v[82:83], s[6:7], 1, v[82:83]
	v_lshl_add_u64 v[82:83], v[82:83], 0, v[144:145]
	global_load_dwordx4 v[112:115], v[82:83], off
	global_load_dwordx4 v[116:119], v[82:83], off offset:32
	global_load_dwordx4 v[120:123], v[82:83], off offset:64
	global_load_dwordx4 v[124:127], v[82:83], off offset:96
	v_lshrrev_b32_e32 v82, 2, v80
	s_and_b32 s6, s8, -16
	v_and_b32_e32 v94, 4, v82
	s_lshl_b32 s7, s1, 3
	s_and_b32 s7, s7, 8
	v_or3_b32 v82, v94, v93, s6
	v_or_b32_e32 v82, s7, v82
	v_mul_lo_u32 v82, v82, s35
	v_or3_b32 v84, v82, v95, v96
	v_or_b32_e32 v82, s8, v92
	v_bitop3_b32 v83, v92, v80, 15 bitop3:0x78
	v_and_b32_e32 v81, 15, v80
	v_mul_lo_u32 v82, v82, s35
	v_lshlrev_b32_e32 v97, 3, v83
	v_or_b32_e32 v88, v82, v97
	v_or_b32_e32 v82, 4, v92
	v_bitop3_b32 v81, v92, v81, 4 bitop3:0x36
	v_or_b32_e32 v82, s8, v82
	v_lshlrev_b32_e32 v98, 3, v81
	v_mul_lo_u32 v82, v82, s35
	s_lshl_b32 s8, s1, 11
	v_lshlrev_b64 v[80:81], 1, v[88:89]
	v_or_b32_e32 v86, v82, v98
	s_add_i32 s27, s8, 0
	s_and_b64 vcc, exec, s[30:31]
	s_cselect_b32 s98, 0x8000, 0
	s_add_i32 s99, s27, s98
	v_lshl_add_u64 v[88:89], s[18:19], 0, v[80:81]
	v_or_b32_e32 v82, 64, v84
	s_add_i32 s8, s27, 0x4000
	v_lshl_add_u64 v[88:89], v[88:89], 0, s[36:37]
	s_mov_b32 m0, s27
	v_lshlrev_b64 v[84:85], 1, v[84:85]
	v_lshlrev_b64 v[86:87], 1, v[86:87]
	s_cbranch_vccz .Lmy_t0_0
	global_load_lds_dwordx4 v[88:89], off
.Lmy_t0_0:
	v_lshl_add_u64 v[88:89], s[20:21], 0, v[84:85]
	s_mov_b32 m0, s8
	v_lshl_add_u64 v[90:91], s[18:19], 0, v[86:87]
	s_cbranch_vccz .Lmy_t0_1
	global_load_lds_dwordx4 v[88:89], off
.Lmy_t0_1:
	v_lshl_add_u64 v[90:91], v[90:91], 0, s[36:37]
	s_add_i32 m0, s27, 0x400
	v_lshl_add_u64 v[88:89], v[88:89], 0, s[94:95]
	s_cbranch_vccz .Lmy_t0_2
	global_load_lds_dwordx4 v[90:91], off
.Lmy_t0_2:
	s_add_i32 m0, s27, 0x4400
	s_add_i32 s8, s99, 0x4000
	s_cbranch_vccz .Lmy_t0_3
	global_load_lds_dwordx4 v[88:89], off
.Lmy_t0_3:
	s_add_i32 m0, s99, 0
	v_lshl_add_u64 v[80:81], s[88:89], 0, v[80:81]
	global_load_lds_dwordx4 v[80:81], off
	v_lshl_add_u64 v[80:81], s[90:91], 0, v[84:85]
	s_mov_b32 m0, s8
	v_mov_b32_e32 v83, v145
	global_load_lds_dwordx4 v[80:81], off
	v_lshl_add_u64 v[80:81], s[88:89], 0, v[86:87]
	s_add_i32 m0, s99, 0x400
	s_nop 0
	global_load_lds_dwordx4 v[80:81], off
	v_lshl_add_u64 v[80:81], v[82:83], 1, s[90:91]
	s_add_i32 m0, s99, 0x4400
	s_nop 0
	global_load_lds_dwordx4 v[80:81], off
	s_waitcnt vmcnt(14)
	v_max_f32_e32 v0, v0, v0
	s_waitcnt vmcnt(13)
	v_max_f32_e32 v1, v1, v1
	v_max_f32_e32 v0, v1, v0
	s_waitcnt vmcnt(11)
	v_max3_f32 v0, v2, v3, v0
	ds_bpermute_b32 v1, v135, v0
	s_waitcnt lgkmcnt(0)
	v_max_f32_e32 v1, v1, v1
	v_max_f32_e32 v0, v0, v1
	ds_bpermute_b32 v1, v142, v0
	s_waitcnt lgkmcnt(0)
	v_max_f32_e32 v1, v1, v1
	v_max_f32_e32 v0, v0, v1
	ds_bpermute_b32 v1, v143, v0
	s_waitcnt lgkmcnt(0)
	v_max_f32_e32 v1, v1, v1
	v_max_f32_e32 v0, v0, v1
	ds_bpermute_b32 v1, v160, v0
	s_waitcnt lgkmcnt(0)
	v_max_f32_e32 v1, v1, v1
	v_max_f32_e32 v0, v0, v1
	ds_bpermute_b32 v1, v161, v0
	s_waitcnt lgkmcnt(0)
	v_max_f32_e32 v1, v1, v1
	v_max_f32_e32 v0, v0, v1
	ds_bpermute_b32 v1, v162, v0
	s_waitcnt lgkmcnt(0)
	v_max_f32_e32 v1, v1, v1
	v_max_f32_e32 v0, v0, v1
	v_add_f32_e32 v0, v164, v0
	v_add_f32_e32 v2, 0x3e800000, v0
	v_cmp_ge_f32_e32 vcc, s0, v2
	s_and_saveexec_b64 s[0:1], vcc
	s_xor_b64 s[40:41], exec, s[0:1]
	s_cbranch_execz .LBB0_341
; __device__ __forceinline__ int v_rd_base(int lane) { return ((lane & 3) << 3) | (((lane >> 2) & 3) << 6) | (((lane >> 4) & 1) << 5) | (((lane >> 5) & 1) << 8); }
; #define WAIT_BAR(N) asm volatile("s_waitcnt vmcnt(" #N ") lgkmcnt(0)\n\ts_barrier" ::: "memory")
; template <bool FIXED> __device__ __forceinline__ void attn_unit(int b, int h, int qb, const bf16* __restrict__ P, bf16* __restrict__ MIX, const float* __restrict__ BT, const float* __restrict__ subg, ...
;     ...
;   for (int i = tid; i < 768; i += 512) btl[i] = BT[(size_t)h * 768 + i] - (FIXED ? sref : 0.f);
;   const float* bt = btl + m * 384 + 128;
;   const float c31 = BT[(size_t)h * 768 + m * 384 + 128 + 127] - (FIXED ? sref : 0.f);
;   f32x16 cfar, czero = f32x16{};
; #pragma unroll
;   for (int r = 0; r < 16; ++r) cfar[r] = FIXED ? c31 : 0.f;
;   float m_reg = -1e30f, l_reg = 0.f; f32x16 o[4] = {}; bf16x8 qr[4];
;   const bf16* Qw = P + (rowbase + qw0 + r32) * PW + h * 128 + m * 64 + hi * 8;
; #pragma unroll
;   for (int d0 = 0; d0 < 4; ++d0) qr[d0] = *reinterpret_cast<const bf16x8*>(Qw + d0 * 16);
;   const bf16* Kh = P + rowbase * PW + 1024 + h * 128; const bf16* Vh = P + rowbase * PW + 2048 + h * 128;
;   unsigned ksrc[2], vsrc[2];
; #pragma unroll
;   for (int i = 0; i < 2; ++i) { const int pk = wid * 2 + i;
;     { const int row = 4 * pk + (lane >> 4), cc = lane & 15; ksrc[i] = (unsigned)(row * PW + ((cc ^ (row & 7)) * 8)); }
;     { const int ob = pk * 1024 + lane * 16, sub = ob >> 9, kk = (sub >> 2) * 8 + ((ob & 511) >> 6), k = (kk & ~0xC) | ((kk & 4) << 1) | ((kk & 8) >> 1), c = (sub & 3) * 32 + ((ob & 63) >> 1);
;       vsrc[i] = (unsigned)(k * PW + c); } }
;   typedef __attribute__((address_space(3))) unsigned lds_u32;
;   typedef __attribute__((address_space(3))) unsigned char lds_u8;
;   lds_u8* const ring = (lds_u8*)lds + wid * 2048;
;     ...
;   const lds_cptr vp0 = (lds_cptr)lds + SHM_K + v_rd_base(lane);
;     ...
;   f32x16 p0, p1; float al, ca; bf16x8 pa0, pa1, pa2, pa3; const int NT = 2 * qb + 2;
;     ...
;   const int NTT = ATT_REP * NT;
;   DMA_TILE(0, 0); DMA_TILE(1, 1);
;   WAIT_BAR(4);
;   int slot = 0;
	v_mov_b32_e32 v0, v169
	s_nop 0
	v_readfirstlane_b32 s25, v0
	s_waitcnt vmcnt(8)
	v_sub_f32_e32 v102, v102, v2
	v_add_u32_e32 v101, s2, v100
	ds_write_b32 v101, v102
	v_cmp_gt_u32_e32 vcc, 0x100, v169
	s_and_saveexec_b64 s[0:1], vcc
	v_sub_f32_e32 v103, v103, v2
	ds_write_b32 v101, v103 offset:2048
	s_mov_b64 exec, s[0:1]
	s_ashr_i32 s1, s25, 6
	s_ashr_i32 s26, s25, 8
	s_and_b32 s24, s1, 3
	s_mul_i32 s6, s26, 0x180
	s_lshl_b32 s0, s24, 5
	s_ashr_i32 s7, s6, 31
	s_or_b32 s29, s0, s34
	s_lshl_b64 s[6:7], s[6:7], 2
	s_add_u32 s6, s10, s6
	s_addc_u32 s7, s11, s7
	v_and_b32_e32 v134, 31, v0
	s_or_b32 s22, s54, s29
	v_bfe_u32 v167, v0, 5, 1
	v_lshlrev_b32_e32 v144, 4, v167
	s_lshl_b32 s8, s1, 3
	v_bfe_u32 v13, v0, 2, 2
	v_and_b32_e32 v168, 63, v0
	v_lshlrev_b32_e32 v166, 3, v168
	v_bfe_u32 v12, v0, 4, 2
	v_and_b32_e32 v15, 32, v0
	v_and_b32_e32 v16, 24, v166
	v_lshlrev_b32_e32 v19, 4, v0
	v_mov_b32_e32 v9, v145
	v_mov_b32_e32 v5, v145
	v_mov_b32_e32 v7, v145
	s_add_i32 s0, s34, s0
	s_lshl_b32 s38, s73, 9
	v_mov_b32_e32 v176, 0
	s_mov_b32 s23, s55
	s_lshl_b32 s28, s73, 1
	s_addk_i32 s29, 0xff51
	v_lshlrev_b32_e32 v171, 8, v134
	s_addk_i32 s38, 0x200
	s_mov_b32 s39, 0
	s_mov_b32 s44, 0
	s_mov_b32 s45, 0
	s_cmp_lg_u64 s[30:31], 0
	s_cselect_b32 s45, 0, 2
	s_mov_b32 s56, 0
	v_mov_b32_e32 v22, v176
	v_mov_b32_e32 v23, v176
	v_mov_b32_e32 v24, v176
	v_mov_b32_e32 v25, v176
	v_mov_b32_e32 v26, v176
	v_mov_b32_e32 v27, v176
	v_mov_b32_e32 v28, v176
	v_mov_b32_e32 v29, v176
	v_mov_b32_e32 v30, v176
	v_mov_b32_e32 v31, v176
	v_mov_b32_e32 v32, 0
	v_mov_b32_e32 v33, v176
	v_mov_b32_e32 v34, v176
	v_mov_b32_e32 v35, v176
	v_mov_b32_e32 v36, v176
	v_mov_b32_e32 v37, v176
	v_mov_b32_e32 v38, v176
	v_mov_b32_e32 v39, v176
	v_mov_b32_e32 v40, v176
	v_mov_b32_e32 v41, v176
	v_mov_b32_e32 v42, v176
	v_mov_b32_e32 v43, v176
	v_mov_b32_e32 v44, v176
	v_mov_b32_e32 v45, v176
	v_mov_b32_e32 v46, v176
	v_mov_b32_e32 v47, v176
	v_mov_b32_e32 v48, 0
	v_mov_b32_e32 v49, v176
	v_mov_b32_e32 v50, v176
	v_mov_b32_e32 v51, v176
	v_mov_b32_e32 v52, v176
	v_mov_b32_e32 v53, v176
	v_mov_b32_e32 v54, v176
	v_mov_b32_e32 v55, v176
	v_mov_b32_e32 v56, v176
	v_mov_b32_e32 v57, v176
	v_mov_b32_e32 v58, v176
	v_mov_b32_e32 v59, v176
	v_mov_b32_e32 v60, v176
	v_mov_b32_e32 v61, v176
	v_mov_b32_e32 v62, v176
	v_mov_b32_e32 v63, v176
	s_waitcnt vmcnt(8)
	v_sub_f32_e32 v64, v104, v2
	v_or_b32_e32 v1, s22, v134
	v_mov_b64_e32 v[2:3], s[16:17]
	v_mad_u64_u32 v[2:3], s[6:7], v1, s70, v[2:3]
	s_lshl_b32 s6, s26, 6
	v_mad_i32_i24 v3, s55, v196, v3
	s_ashr_i32 s7, s6, 31
	v_lshl_add_u64 v[2:3], s[6:7], 1, v[2:3]
	v_lshl_add_u64 v[2:3], v[2:3], 0, v[144:145]
	v_lshrrev_b32_e32 v2, 2, v0
	s_and_b32 s6, s8, -16
	v_and_b32_e32 v14, 4, v2
	s_lshl_b32 s7, s1, 3
	s_and_b32 s7, s7, 8
	v_or3_b32 v2, v14, v13, s6
	v_or_b32_e32 v2, s7, v2
	v_mul_lo_u32 v2, v2, s35
	v_or3_b32 v4, v2, v15, v16
	v_or_b32_e32 v2, s8, v12
	v_bitop3_b32 v3, v12, v0, 15 bitop3:0x78
	v_and_b32_e32 v1, 15, v0
	v_mul_lo_u32 v2, v2, s35
	v_lshlrev_b32_e32 v17, 3, v3
	v_or_b32_e32 v8, v2, v17
	v_or_b32_e32 v2, 4, v12
	v_bitop3_b32 v1, v12, v1, 4 bitop3:0x36
	v_or_b32_e32 v2, s8, v2
	v_lshlrev_b32_e32 v18, 3, v1
	v_and_b32_e32 v1, 0xc0, v19
	v_lshlrev_b32_e32 v0, 1, v0
	v_mul_lo_u32 v2, v2, s35
	s_lshl_b32 s8, s1, 11
	v_and_b32_e32 v20, 32, v0
	v_add3_u32 v21, 0, v16, v1
	v_lshlrev_b64 v[0:1], 1, v[8:9]
	v_or_b32_e32 v6, v2, v18
	s_add_i32 s27, s8, 0
	v_lshl_add_u64 v[8:9], s[18:19], 0, v[0:1]
	v_or_b32_e32 v2, 64, v4
	s_add_i32 s8, s27, 0x4000
	v_lshl_add_u64 v[8:9], v[8:9], 0, s[36:37]
	s_mov_b32 m0, s27
	v_lshlrev_b64 v[4:5], 1, v[4:5]
	v_lshlrev_b64 v[6:7], 1, v[6:7]
	v_lshl_add_u64 v[8:9], s[20:21], 0, v[4:5]
	s_mov_b32 m0, s8
	v_lshl_add_u64 v[10:11], s[18:19], 0, v[6:7]
	v_lshl_add_u64 v[10:11], v[10:11], 0, s[36:37]
	s_add_i32 m0, s27, 0x400
	v_lshl_add_u64 v[8:9], v[8:9], 0, s[94:95]
	s_add_i32 m0, s27, 0x4400
	s_add_i32 s8, s27, 0xc000
	s_add_i32 m0, s27, 0x8000
	v_lshl_add_u64 v[0:1], s[88:89], 0, v[0:1]
	v_lshl_add_u64 v[0:1], s[90:91], 0, v[4:5]
	s_mov_b32 m0, s8
	v_mov_b32_e32 v3, v145
	v_lshl_add_u64 v[0:1], s[88:89], 0, v[6:7]
	s_add_i32 m0, s27, 0x8400
	s_lshl_b32 s8, s26, 7
	v_lshl_add_u64 v[0:1], v[2:3], 1, s[90:91]
	s_add_i32 m0, s27, 0xc400
	s_mul_i32 s1, s1, 0xc000
	v_or_b32_e32 v0, s8, v144
	v_and_b32_e32 v1, 0x70, v19
	v_bitop3_b32 v173, v0, v1, 32 bitop3:0x36
	v_bitop3_b32 v174, v0, v1, 64 bitop3:0x36
	v_bitop3_b32 v175, v0, v1, s64 bitop3:0x36
	v_or_b32_e32 v0, s6, v14
	v_or3_b32 v0, v0, s7, v13
	v_mul_lo_u32 v0, v0, s35
	v_bitop3_b32 v172, s8, v1, v144 bitop3:0x36
	v_add_u32_e32 v172, v172, v171
	v_add_u32_e32 v173, v173, v171
	v_add_u32_e32 v174, v174, v171
	v_add_u32_e32 v175, v175, v171
	v_or3_b32 v0, v0, v15, v16
	v_mov_b32_e32 v1, v145
	s_add_i32 s6, s1, 0x6000
	v_lshlrev_b64 v[136:137], 1, v[0:1]
	v_mov_b32_e32 v0, s6
	v_mad_u32_u24 v0, v12, s35, v0
	v_or_b32_e32 v0, v0, v18
	v_lshlrev_b32_e32 v138, 1, v0
	v_mov_b32_e32 v0, s1
	v_mad_u32_u24 v0, v12, s35, v0
	v_or_b32_e32 v0, v0, v17
	s_waitcnt vmcnt(4) lgkmcnt(0)
	s_barrier
	v_lshlrev_b32_e32 v2, 2, v167
	v_lshlrev_b32_e32 v140, 1, v0
	s_mul_i32 s1, s26, 0x600
	v_add_u32_e32 v0, s0, v134
	v_and_b32_e32 v8, 0x100, v166
	v_sub_u32_e32 v0, v0, v2
	s_add_i32 s0, s1, 0
	v_mov_b32_e32 v65, v64
	v_mov_b32_e32 v66, v64
	v_mov_b32_e32 v67, v64
	v_mov_b32_e32 v68, v64
	v_mov_b32_e32 v69, v64
	v_mov_b32_e32 v70, v64
	v_mov_b32_e32 v71, v64
	v_mov_b32_e32 v72, v64
	v_mov_b32_e32 v73, v64
	v_mov_b32_e32 v74, v64
	v_mov_b32_e32 v75, v64
	v_mov_b32_e32 v76, v64
	v_mov_b32_e32 v77, v64
	v_mov_b32_e32 v78, v64
	v_mov_b32_e32 v79, v64
	v_add3_u32 v170, v21, v20, v8
	v_lshl_add_u32 v178, v0, 2, s0
	s_mov_b64 s[0:1], s[92:93]
	v_mov_b32_e32 v0, 0
	v_mov_b32_e32 v1, v176
	v_mov_b32_e32 v2, v176
	v_mov_b32_e32 v3, v176
	v_mov_b32_e32 v4, v176
	v_mov_b32_e32 v5, v176
	v_mov_b32_e32 v6, v176
	v_mov_b32_e32 v7, v176
	v_mov_b32_e32 v8, v176
	v_mov_b32_e32 v9, v176
	v_mov_b32_e32 v10, v176
	v_mov_b32_e32 v11, v176
	v_mov_b32_e32 v12, v176
	v_mov_b32_e32 v13, v176
	v_mov_b32_e32 v14, v176
	v_mov_b32_e32 v15, v176
	v_mov_b32_e32 v16, 0
	v_mov_b32_e32 v17, v176
	v_mov_b32_e32 v18, v176
	v_mov_b32_e32 v19, v176
	v_mov_b32_e32 v20, v176
	v_mov_b32_e32 v21, v176
	s_waitcnt vmcnt(4)
	s_branch .LBB0_312

; template <bool FIXED> __device__ __forceinline__ void attn_unit(int b, int h, int qb, const bf16* __restrict__ P, bf16* __restrict__ MIX, const float* __restrict__ BT, const float* __restrict__ subg, ...
;     ...
;     bf16* Ow = MIX + (rowbase + qw0) * DMODEL + h * 128 + r32;
;     float gsub[4];
; #pragma unroll
;     for (int d0 = 0; d0 < 4; ++d0) gsub[d0] = subg[d0 * 32 + r32] * post;
.LBB0_328:
	s_cmpk_gt_u32 s25, 0xff
	s_waitcnt lgkmcnt(0)
	s_barrier
	s_cbranch_scc1 .LBB0_330
	v_lshlrev_b32_e32 v65, 2, v134
	global_load_dword v69, v65, s[50:51]
	global_load_dword v67, v65, s[50:51] offset:128
	global_load_dword v68, v65, s[50:51] offset:256
	global_load_dword v70, v65, s[50:51] offset:384
	s_and_b64 vcc, exec, s[30:31]
	s_cbranch_vccz .Lmy_nopf_a
	s_add_u32 s98, s92, 0x1a200800
	s_addc_u32 s99, s93, 0
	s_sub_u32 s100, s92, 0x180000
	s_subb_u32 s101, s93, 0
	s_add_u32 s100, s100, s4
	s_addc_u32 s101, s101, s5
	s_add_i32 m0, s27, 0x10000
	s_nop 0
	global_load_lds_dwordx4 v140, s[98:99]
	s_add_i32 m0, s27, 0x14000
	s_nop 0
	global_load_lds_dwordx4 v136, s[100:101]
	s_add_i32 m0, s27, 0x10400
	s_sub_u32 s100, s92, 0x180000
	s_subb_u32 s101, s93, 0
	s_add_u32 s100, s100, s74
	s_addc_u32 s101, s101, s75
	global_load_lds_dwordx4 v138, s[98:99]
	s_add_i32 m0, s27, 0x14400
	s_nop 0
	global_load_lds_dwordx4 v136, s[100:101]
.Lmy_nopf_a:
	ds_read2st64_b32 v[88:89], v72 offset1:1
	ds_read2st64_b32 v[90:91], v72 offset0:2 offset1:3
	ds_read2st64_b32 v[92:93], v72 offset0:4 offset1:5
	ds_read2st64_b32 v[94:95], v72 offset0:6 offset1:7
	ds_read2st64_b32 v[96:97], v72 offset0:8 offset1:9
	ds_read2st64_b32 v[98:99], v72 offset0:10 offset1:11
	ds_read2st64_b32 v[100:101], v72 offset0:12 offset1:13
	ds_read2st64_b32 v[102:103], v72 offset0:14 offset1:15
	ds_read2st64_b32 v[104:105], v72 offset0:16 offset1:17
	ds_read2st64_b32 v[106:107], v72 offset0:18 offset1:19
	ds_read2st64_b32 v[108:109], v72 offset0:20 offset1:21
	ds_read2st64_b32 v[110:111], v72 offset0:22 offset1:23
	ds_read2st64_b32 v[112:113], v72 offset0:24 offset1:25
	ds_read2st64_b32 v[114:115], v72 offset0:26 offset1:27
	ds_read2st64_b32 v[116:117], v72 offset0:28 offset1:29
	ds_read2st64_b32 v[118:119], v72 offset0:30 offset1:31
	ds_read2st64_b32 v[120:121], v72 offset0:32 offset1:33
	ds_read2st64_b32 v[122:123], v72 offset0:34 offset1:35
	ds_read2st64_b32 v[124:125], v72 offset0:36 offset1:37
	ds_read2st64_b32 v[126:127], v72 offset0:38 offset1:39
	ds_read2st64_b32 v[198:199], v72 offset0:40 offset1:41
	ds_read2st64_b32 v[200:201], v72 offset0:42 offset1:43
	ds_read2st64_b32 v[202:203], v72 offset0:44 offset1:45
	ds_read2st64_b32 v[204:205], v72 offset0:46 offset1:47
	ds_read2st64_b32 v[206:207], v72 offset0:48 offset1:49
	ds_read2st64_b32 v[208:209], v72 offset0:50 offset1:51
	ds_read2st64_b32 v[210:211], v72 offset0:52 offset1:53
	ds_read2st64_b32 v[212:213], v72 offset0:54 offset1:55
	ds_read2st64_b32 v[214:215], v72 offset0:56 offset1:57
	ds_read2st64_b32 v[216:217], v72 offset0:58 offset1:59
	ds_read2st64_b32 v[218:219], v72 offset0:60 offset1:61
	ds_read2st64_b32 v[220:221], v72 offset0:62 offset1:63
	s_lshl_b64 s[0:1], s[22:23], 12
	s_add_u32 s0, s68, s0
	s_addc_u32 s1, s69, s1
	v_lshlrev_b32_e32 v144, 1, v134
	v_lshl_add_u64 v[86:87], s[0:1], 0, v[144:145]
	v_lshlrev_b32_e32 v144, 14, v167
	v_lshl_add_u64 v[86:87], v[86:87], 0, v[144:145]
	s_waitcnt lgkmcnt(15)
	v_fma_f32 v0, v0, v64, -v88
	v_fma_f32 v1, v1, v85, -v89
	v_fma_f32 v2, v2, v84, -v90
	v_fma_f32 v3, v3, v83, -v91
	v_fma_f32 v4, v4, v82, -v92
	v_fma_f32 v5, v5, v81, -v93
	v_fma_f32 v6, v6, v80, -v94
	v_fma_f32 v7, v7, v79, -v95
	v_fma_f32 v8, v8, v78, -v96
	v_fma_f32 v9, v9, v77, -v97
	v_fma_f32 v10, v10, v76, -v98
	v_fma_f32 v11, v11, v75, -v99
	v_fma_f32 v12, v12, v74, -v100
	v_fma_f32 v13, v13, v73, -v101
	v_fma_f32 v14, v14, v71, -v102
	v_fma_f32 v15, v15, v66, -v103
	s_waitcnt lgkmcnt(15)
	v_fma_f32 v16, v16, v64, -v104
	v_fma_f32 v17, v17, v85, -v105
	v_fma_f32 v18, v18, v84, -v106
	v_fma_f32 v19, v19, v83, -v107
	v_fma_f32 v20, v20, v82, -v108
	v_fma_f32 v21, v21, v81, -v109
	v_fma_f32 v22, v22, v80, -v110
	v_fma_f32 v23, v23, v79, -v111
	v_fma_f32 v24, v24, v78, -v112
	v_fma_f32 v25, v25, v77, -v113
	v_fma_f32 v26, v26, v76, -v114
	v_fma_f32 v27, v27, v75, -v115
	v_fma_f32 v28, v28, v74, -v116
	v_fma_f32 v29, v29, v73, -v117
	v_fma_f32 v30, v30, v71, -v118
	v_fma_f32 v31, v31, v66, -v119
	s_waitcnt lgkmcnt(8)
	v_fma_f32 v32, v32, v64, -v120
	v_fma_f32 v33, v33, v85, -v121
	v_fma_f32 v34, v34, v84, -v122
	v_fma_f32 v35, v35, v83, -v123
	v_fma_f32 v36, v36, v82, -v124
	v_fma_f32 v37, v37, v81, -v125
	v_fma_f32 v38, v38, v80, -v126
	v_fma_f32 v39, v39, v79, -v127
	v_fma_f32 v40, v40, v78, -v198
	v_fma_f32 v41, v41, v77, -v199
	v_fma_f32 v42, v42, v76, -v200
	v_fma_f32 v43, v43, v75, -v201
	v_fma_f32 v44, v44, v74, -v202
	v_fma_f32 v45, v45, v73, -v203
	v_fma_f32 v46, v46, v71, -v204
	v_fma_f32 v47, v47, v66, -v205
	s_waitcnt lgkmcnt(0)
; template <bool FIXED> __device__ __forceinline__ void attn_unit(int b, int h, int qb, const bf16* __restrict__ P, bf16* __restrict__ MIX, const float* __restrict__ BT, const float* __restrict__ subg, ...
;     ...
;     for (int r = 0; r < 16; ++r) { float y[4]; float ss = 0.f;
; #pragma unroll
;       for (int d0 = 0; d0 < 4; ++d0) { y[d0] = o[d0][r] * rli[r] - xch[(d0 * 16 + r) * 64]; ss += y[d0] * y[d0]; }
;       ss += __shfl_xor(ss, 1); ss += __shfl_xor(ss, 2); ss += __shfl_xor(ss, 4); ss += __shfl_xor(ss, 8); ss += __shfl_xor(ss, 16);
	v_fma_f32 v48, v48, v64, -v206
	v_fma_f32 v49, v49, v85, -v207
	v_fma_f32 v50, v50, v84, -v208
	v_fma_f32 v51, v51, v83, -v209
	v_fma_f32 v52, v52, v82, -v210
	v_fma_f32 v53, v53, v81, -v211
	v_fma_f32 v54, v54, v80, -v212
	v_fma_f32 v55, v55, v79, -v213
	v_fma_f32 v56, v56, v78, -v214
	v_fma_f32 v57, v57, v77, -v215
	v_fma_f32 v58, v58, v76, -v216
	v_fma_f32 v59, v59, v75, -v217
	v_fma_f32 v60, v60, v74, -v218
	v_fma_f32 v61, v61, v73, -v219
	v_fma_f32 v62, v62, v71, -v220
	v_fma_f32 v63, v63, v66, -v221
	v_mul_f32_e32 v222, v16, v16
	v_mul_f32_e32 v223, v17, v17
	v_mul_f32_e32 v224, v18, v18
	v_mul_f32_e32 v225, v19, v19
	v_mul_f32_e32 v226, v20, v20
	v_mul_f32_e32 v227, v21, v21
	v_mul_f32_e32 v228, v22, v22
	v_mul_f32_e32 v229, v23, v23
	v_mul_f32_e32 v230, v24, v24
	v_mul_f32_e32 v231, v25, v25
	v_mul_f32_e32 v232, v26, v26
	v_mul_f32_e32 v233, v27, v27
	v_mul_f32_e32 v234, v28, v28
	v_mul_f32_e32 v235, v29, v29
	v_mul_f32_e32 v236, v30, v30
	v_mul_f32_e32 v237, v31, v31
	v_fmac_f32_e32 v222, v0, v0
	v_fmac_f32_e32 v223, v1, v1
	v_fmac_f32_e32 v224, v2, v2
	v_fmac_f32_e32 v225, v3, v3
	v_fmac_f32_e32 v226, v4, v4
	v_fmac_f32_e32 v227, v5, v5
	v_fmac_f32_e32 v228, v6, v6
	v_fmac_f32_e32 v229, v7, v7
	v_fmac_f32_e32 v230, v8, v8
	v_fmac_f32_e32 v231, v9, v9
	v_fmac_f32_e32 v232, v10, v10
	v_fmac_f32_e32 v233, v11, v11
	v_fmac_f32_e32 v234, v12, v12
	v_fmac_f32_e32 v235, v13, v13
	v_fmac_f32_e32 v236, v14, v14
	v_fmac_f32_e32 v237, v15, v15
	v_fmac_f32_e32 v222, v32, v32
	v_fmac_f32_e32 v223, v33, v33
	v_fmac_f32_e32 v224, v34, v34
	v_fmac_f32_e32 v225, v35, v35
	v_fmac_f32_e32 v226, v36, v36
	v_fmac_f32_e32 v227, v37, v37
	v_fmac_f32_e32 v228, v38, v38
	v_fmac_f32_e32 v229, v39, v39
	v_fmac_f32_e32 v230, v40, v40
	v_fmac_f32_e32 v231, v41, v41
	v_fmac_f32_e32 v232, v42, v42
	v_fmac_f32_e32 v233, v43, v43
	v_fmac_f32_e32 v234, v44, v44
	v_fmac_f32_e32 v235, v45, v45
	v_fmac_f32_e32 v236, v46, v46
	v_fmac_f32_e32 v237, v47, v47
	v_fmac_f32_e32 v222, v48, v48
	v_fmac_f32_e32 v223, v49, v49
	v_fmac_f32_e32 v224, v50, v50
	v_fmac_f32_e32 v225, v51, v51
	v_fmac_f32_e32 v226, v52, v52
	v_fmac_f32_e32 v227, v53, v53
	v_fmac_f32_e32 v228, v54, v54
	v_fmac_f32_e32 v229, v55, v55
	v_fmac_f32_e32 v230, v56, v56
	v_fmac_f32_e32 v231, v57, v57
	v_fmac_f32_e32 v232, v58, v58
	v_fmac_f32_e32 v233, v59, v59
	v_fmac_f32_e32 v234, v60, v60
	v_fmac_f32_e32 v235, v61, v61
	v_fmac_f32_e32 v236, v62, v62
	v_fmac_f32_e32 v237, v63, v63
	ds_bpermute_b32 v238, v135, v222
	ds_bpermute_b32 v239, v135, v223
	ds_bpermute_b32 v240, v135, v224
	ds_bpermute_b32 v241, v135, v225
	ds_bpermute_b32 v242, v135, v226
	ds_bpermute_b32 v243, v135, v227
	ds_bpermute_b32 v244, v135, v228
	ds_bpermute_b32 v245, v135, v229
	ds_bpermute_b32 v246, v135, v230
	ds_bpermute_b32 v247, v135, v231
	ds_bpermute_b32 v248, v135, v232
	ds_bpermute_b32 v249, v135, v233
	ds_bpermute_b32 v250, v135, v234
	ds_bpermute_b32 v251, v135, v235
	ds_bpermute_b32 v252, v135, v236
	ds_bpermute_b32 v253, v135, v237
	s_waitcnt lgkmcnt(15)
	v_add_f32_e32 v222, v222, v238
	s_waitcnt lgkmcnt(14)
	v_add_f32_e32 v223, v223, v239
	s_waitcnt lgkmcnt(13)
	v_add_f32_e32 v224, v224, v240
	s_waitcnt lgkmcnt(12)
	v_add_f32_e32 v225, v225, v241
	s_waitcnt lgkmcnt(11)
	v_add_f32_e32 v226, v226, v242
	s_waitcnt lgkmcnt(10)
	v_add_f32_e32 v227, v227, v243
	s_waitcnt lgkmcnt(9)
	v_add_f32_e32 v228, v228, v244
	s_waitcnt lgkmcnt(8)
	v_add_f32_e32 v229, v229, v245
	s_waitcnt lgkmcnt(7)
	v_add_f32_e32 v230, v230, v246
	s_waitcnt lgkmcnt(6)
	v_add_f32_e32 v231, v231, v247
	s_waitcnt lgkmcnt(5)
	v_add_f32_e32 v232, v232, v248
	s_waitcnt lgkmcnt(4)
	v_add_f32_e32 v233, v233, v249
	s_waitcnt lgkmcnt(3)
	v_add_f32_e32 v234, v234, v250
	s_waitcnt lgkmcnt(2)
	v_add_f32_e32 v235, v235, v251
	s_waitcnt lgkmcnt(1)
	v_add_f32_e32 v236, v236, v252
	s_waitcnt lgkmcnt(0)
	v_add_f32_e32 v237, v237, v253
	ds_bpermute_b32 v238, v142, v222
	ds_bpermute_b32 v239, v142, v223
	ds_bpermute_b32 v240, v142, v224
	ds_bpermute_b32 v241, v142, v225
	ds_bpermute_b32 v242, v142, v226
	ds_bpermute_b32 v243, v142, v227
	ds_bpermute_b32 v244, v142, v228
	ds_bpermute_b32 v245, v142, v229
	ds_bpermute_b32 v246, v142, v230
	ds_bpermute_b32 v247, v142, v231
	ds_bpermute_b32 v248, v142, v232
	ds_bpermute_b32 v249, v142, v233
	ds_bpermute_b32 v250, v142, v234
	ds_bpermute_b32 v251, v142, v235
	ds_bpermute_b32 v252, v142, v236
	ds_bpermute_b32 v253, v142, v237
	s_waitcnt lgkmcnt(15)
	v_add_f32_e32 v222, v222, v238
	s_waitcnt lgkmcnt(14)
	v_add_f32_e32 v223, v223, v239
	s_waitcnt lgkmcnt(13)
	v_add_f32_e32 v224, v224, v240
	s_waitcnt lgkmcnt(12)
	v_add_f32_e32 v225, v225, v241
	s_waitcnt lgkmcnt(11)
	v_add_f32_e32 v226, v226, v242
	s_waitcnt lgkmcnt(10)
	v_add_f32_e32 v227, v227, v243
	s_waitcnt lgkmcnt(9)
	v_add_f32_e32 v228, v228, v244
	s_waitcnt lgkmcnt(8)
; template <bool FIXED> __device__ __forceinline__ void attn_unit(int b, int h, int qb, const bf16* __restrict__ P, bf16* __restrict__ MIX, const float* __restrict__ BT, const float* __restrict__ subg, ...
;     ...
;       ss += __shfl_xor(ss, 1); ss += __shfl_xor(ss, 2); ss += __shfl_xor(ss, 4); ss += __shfl_xor(ss, 8); ss += __shfl_xor(ss, 16);
	v_add_f32_e32 v229, v229, v245
	s_waitcnt lgkmcnt(7)
	v_add_f32_e32 v230, v230, v246
	s_waitcnt lgkmcnt(6)
	v_add_f32_e32 v231, v231, v247
	s_waitcnt lgkmcnt(5)
	v_add_f32_e32 v232, v232, v248
	s_waitcnt lgkmcnt(4)
	v_add_f32_e32 v233, v233, v249
	s_waitcnt lgkmcnt(3)
	v_add_f32_e32 v234, v234, v250
	s_waitcnt lgkmcnt(2)
	v_add_f32_e32 v235, v235, v251
	s_waitcnt lgkmcnt(1)
	v_add_f32_e32 v236, v236, v252
	s_waitcnt lgkmcnt(0)
	v_add_f32_e32 v237, v237, v253
	ds_bpermute_b32 v238, v143, v222
	ds_bpermute_b32 v239, v143, v223
	ds_bpermute_b32 v240, v143, v224
	ds_bpermute_b32 v241, v143, v225
	ds_bpermute_b32 v242, v143, v226
	ds_bpermute_b32 v243, v143, v227
	ds_bpermute_b32 v244, v143, v228
	ds_bpermute_b32 v245, v143, v229
	ds_bpermute_b32 v246, v143, v230
	ds_bpermute_b32 v247, v143, v231
	ds_bpermute_b32 v248, v143, v232
	ds_bpermute_b32 v249, v143, v233
	ds_bpermute_b32 v250, v143, v234
	ds_bpermute_b32 v251, v143, v235
	ds_bpermute_b32 v252, v143, v236
	ds_bpermute_b32 v253, v143, v237
	s_waitcnt lgkmcnt(15)
	v_add_f32_e32 v222, v222, v238
	s_waitcnt lgkmcnt(14)
	v_add_f32_e32 v223, v223, v239
	s_waitcnt lgkmcnt(13)
	v_add_f32_e32 v224, v224, v240
	s_waitcnt lgkmcnt(12)
	v_add_f32_e32 v225, v225, v241
	s_waitcnt lgkmcnt(11)
	v_add_f32_e32 v226, v226, v242
	s_waitcnt lgkmcnt(10)
	v_add_f32_e32 v227, v227, v243
	s_waitcnt lgkmcnt(9)
	v_add_f32_e32 v228, v228, v244
	s_waitcnt lgkmcnt(8)
	v_add_f32_e32 v229, v229, v245
	s_waitcnt lgkmcnt(7)
	v_add_f32_e32 v230, v230, v246
	s_waitcnt lgkmcnt(6)
	v_add_f32_e32 v231, v231, v247
	s_waitcnt lgkmcnt(5)
	v_add_f32_e32 v232, v232, v248
	s_waitcnt lgkmcnt(4)
	v_add_f32_e32 v233, v233, v249
	s_waitcnt lgkmcnt(3)
	v_add_f32_e32 v234, v234, v250
	s_waitcnt lgkmcnt(2)
	v_add_f32_e32 v235, v235, v251
	s_waitcnt lgkmcnt(1)
	v_add_f32_e32 v236, v236, v252
	s_waitcnt lgkmcnt(0)
	v_add_f32_e32 v237, v237, v253
	ds_bpermute_b32 v238, v160, v222
	ds_bpermute_b32 v239, v160, v223
	ds_bpermute_b32 v240, v160, v224
	ds_bpermute_b32 v241, v160, v225
	ds_bpermute_b32 v242, v160, v226
	ds_bpermute_b32 v243, v160, v227
	ds_bpermute_b32 v244, v160, v228
	ds_bpermute_b32 v245, v160, v229
	ds_bpermute_b32 v246, v160, v230
	ds_bpermute_b32 v247, v160, v231
	ds_bpermute_b32 v248, v160, v232
	ds_bpermute_b32 v249, v160, v233
	ds_bpermute_b32 v250, v160, v234
	ds_bpermute_b32 v251, v160, v235
	ds_bpermute_b32 v252, v160, v236
	ds_bpermute_b32 v253, v160, v237
	s_waitcnt lgkmcnt(15)
	v_add_f32_e32 v222, v222, v238
	s_waitcnt lgkmcnt(14)
	v_add_f32_e32 v223, v223, v239
	s_waitcnt lgkmcnt(13)
	v_add_f32_e32 v224, v224, v240
	s_waitcnt lgkmcnt(12)
	v_add_f32_e32 v225, v225, v241
	s_waitcnt lgkmcnt(11)
	v_add_f32_e32 v226, v226, v242
	s_waitcnt lgkmcnt(10)
	v_add_f32_e32 v227, v227, v243
	s_waitcnt lgkmcnt(9)
	v_add_f32_e32 v228, v228, v244
	s_waitcnt lgkmcnt(8)
	v_add_f32_e32 v229, v229, v245
	s_waitcnt lgkmcnt(7)
	v_add_f32_e32 v230, v230, v246
	s_waitcnt lgkmcnt(6)
	v_add_f32_e32 v231, v231, v247
	s_waitcnt lgkmcnt(5)
	v_add_f32_e32 v232, v232, v248
	s_waitcnt lgkmcnt(4)
	v_add_f32_e32 v233, v233, v249
	s_waitcnt lgkmcnt(3)
	v_add_f32_e32 v234, v234, v250
	s_waitcnt lgkmcnt(2)
	v_add_f32_e32 v235, v235, v251
	s_waitcnt lgkmcnt(1)
	v_add_f32_e32 v236, v236, v252
	s_waitcnt lgkmcnt(0)
	v_add_f32_e32 v237, v237, v253
	ds_bpermute_b32 v238, v161, v222
	ds_bpermute_b32 v239, v161, v223
	ds_bpermute_b32 v240, v161, v224
	ds_bpermute_b32 v241, v161, v225
	ds_bpermute_b32 v242, v161, v226
	ds_bpermute_b32 v243, v161, v227
	ds_bpermute_b32 v244, v161, v228
	ds_bpermute_b32 v245, v161, v229
	ds_bpermute_b32 v246, v161, v230
	ds_bpermute_b32 v247, v161, v231
	ds_bpermute_b32 v248, v161, v232
	ds_bpermute_b32 v249, v161, v233
	ds_bpermute_b32 v250, v161, v234
	ds_bpermute_b32 v251, v161, v235
	ds_bpermute_b32 v252, v161, v236
	ds_bpermute_b32 v253, v161, v237
	s_waitcnt lgkmcnt(15)
	v_add_f32_e32 v222, v222, v238
	s_waitcnt lgkmcnt(14)
	v_add_f32_e32 v223, v223, v239
	s_waitcnt lgkmcnt(13)
	v_add_f32_e32 v224, v224, v240
	s_waitcnt lgkmcnt(12)
	v_add_f32_e32 v225, v225, v241
	s_waitcnt lgkmcnt(11)
	v_add_f32_e32 v226, v226, v242
	s_waitcnt lgkmcnt(10)
	v_add_f32_e32 v227, v227, v243
	s_waitcnt lgkmcnt(9)
	v_add_f32_e32 v228, v228, v244
	s_waitcnt lgkmcnt(8)
	v_add_f32_e32 v229, v229, v245
	s_waitcnt lgkmcnt(7)
	v_add_f32_e32 v230, v230, v246
	s_waitcnt lgkmcnt(6)
	v_add_f32_e32 v231, v231, v247
	s_waitcnt lgkmcnt(5)
	v_add_f32_e32 v232, v232, v248
	s_waitcnt lgkmcnt(4)
	v_add_f32_e32 v233, v233, v249
	s_waitcnt lgkmcnt(3)
	v_add_f32_e32 v234, v234, v250
	s_waitcnt lgkmcnt(2)
	v_add_f32_e32 v235, v235, v251
	s_waitcnt lgkmcnt(1)
	v_add_f32_e32 v236, v236, v252
	s_waitcnt lgkmcnt(0)
	v_add_f32_e32 v237, v237, v253
	s_and_b64 vcc, exec, s[30:31]
	s_cbranch_vccz .Lmy_w0_a
	s_waitcnt vmcnt(4)
	s_branch .Lmy_w1_a

; __device__ __forceinline__ int crow(int r, int hi) { return (r & 3) + 8 * (r >> 2) + 4 * hi; }
; template <bool FIXED> __device__ __forceinline__ void attn_unit(int b, int h, int qb, const bf16* __restrict__ P, bf16* __restrict__ MIX, const float* __restrict__ BT, const float* __restrict__ subg, ...
;     ...
;     for (int d0 = 0; d0 < 4; ++d0) gsub[d0] = subg[d0 * 32 + r32] * post;
; #pragma unroll
;     for (int r = 0; r < 16; ++r) { float y[4]; float ss = 0.f;
; #pragma unroll
;       for (int d0 = 0; d0 < 4; ++d0) { y[d0] = o[d0][r] * rli[r] - xch[(d0 * 16 + r) * 64]; ss += y[d0] * y[d0]; }
;       ss += __shfl_xor(ss, 1); ss += __shfl_xor(ss, 2); ss += __shfl_xor(ss, 4); ss += __shfl_xor(ss, 8); ss += __shfl_xor(ss, 16);
;       const float rs = 1.0f / sqrtf(ss * (1.0f / 128.0f) + 1e-6f);
; #pragma unroll
;       for (int d0 = 0; d0 < 4; ++d0) Ow[(long)crow(r, hi) * DMODEL + d0 * 32] = __float2bfloat16(y[d0] * rs * gsub[d0]); }
.Lmy_w1_a:
	v_mul_f32_e32 v69, v165, v69
	v_mul_f32_e32 v67, v165, v67
	v_mul_f32_e32 v68, v165, v68
	v_mul_f32_e32 v70, v165, v70
	v_fmamk_f32 v222, v222, 0x3c000000, v186
	v_rsq_f32_e32 v222, v222
	v_fmamk_f32 v223, v223, 0x3c000000, v186
	v_rsq_f32_e32 v223, v223
	v_fmamk_f32 v224, v224, 0x3c000000, v186
	v_rsq_f32_e32 v224, v224
	v_fmamk_f32 v225, v225, 0x3c000000, v186
	v_rsq_f32_e32 v225, v225
	v_fmamk_f32 v226, v226, 0x3c000000, v186
	v_rsq_f32_e32 v226, v226
	v_fmamk_f32 v227, v227, 0x3c000000, v186
	v_rsq_f32_e32 v227, v227
	v_fmamk_f32 v228, v228, 0x3c000000, v186
	v_rsq_f32_e32 v228, v228
	v_fmamk_f32 v229, v229, 0x3c000000, v186
	v_rsq_f32_e32 v229, v229
	v_fmamk_f32 v230, v230, 0x3c000000, v186
	v_rsq_f32_e32 v230, v230
	v_fmamk_f32 v231, v231, 0x3c000000, v186
	v_rsq_f32_e32 v231, v231
	v_fmamk_f32 v232, v232, 0x3c000000, v186
	v_rsq_f32_e32 v232, v232
	v_fmamk_f32 v233, v233, 0x3c000000, v186
	v_rsq_f32_e32 v233, v233
	v_fmamk_f32 v234, v234, 0x3c000000, v186
	v_rsq_f32_e32 v234, v234
	v_fmamk_f32 v235, v235, 0x3c000000, v186
	v_rsq_f32_e32 v235, v235
	v_fmamk_f32 v236, v236, 0x3c000000, v186
	v_rsq_f32_e32 v236, v236
	v_fmamk_f32 v237, v237, 0x3c000000, v186
	v_rsq_f32_e32 v237, v237
	v_mov_b32_e32 v88, v86
	v_mov_b32_e32 v89, v87
	v_add_co_u32_e32 v90, vcc, 0x1000, v86
	v_addc_co_u32_e32 v91, vcc, 0, v87, vcc
	v_add_co_u32_e32 v92, vcc, 0x2000, v86
	v_addc_co_u32_e32 v93, vcc, 0, v87, vcc
	v_add_co_u32_e32 v94, vcc, 0x3000, v86
	v_addc_co_u32_e32 v95, vcc, 0, v87, vcc
	v_add_co_u32_e32 v96, vcc, 0x8000, v86
	v_addc_co_u32_e32 v97, vcc, 0, v87, vcc
	v_add_co_u32_e32 v98, vcc, 0x9000, v86
	v_addc_co_u32_e32 v99, vcc, 0, v87, vcc
	v_add_co_u32_e32 v100, vcc, 0xa000, v86
	v_addc_co_u32_e32 v101, vcc, 0, v87, vcc
	v_add_co_u32_e32 v102, vcc, 0xb000, v86
	v_addc_co_u32_e32 v103, vcc, 0, v87, vcc
	v_add_co_u32_e32 v104, vcc, 0x10000, v86
	v_addc_co_u32_e32 v105, vcc, 0, v87, vcc
	v_add_co_u32_e32 v106, vcc, 0x11000, v86
	v_addc_co_u32_e32 v107, vcc, 0, v87, vcc
	v_add_co_u32_e32 v108, vcc, 0x12000, v86
	v_addc_co_u32_e32 v109, vcc, 0, v87, vcc
	v_add_co_u32_e32 v110, vcc, 0x13000, v86
	v_addc_co_u32_e32 v111, vcc, 0, v87, vcc
	v_add_co_u32_e32 v112, vcc, 0x18000, v86
	v_addc_co_u32_e32 v113, vcc, 0, v87, vcc
	v_add_co_u32_e32 v114, vcc, 0x19000, v86
	v_addc_co_u32_e32 v115, vcc, 0, v87, vcc
	v_add_co_u32_e32 v116, vcc, 0x1a000, v86
	v_addc_co_u32_e32 v117, vcc, 0, v87, vcc
	v_add_co_u32_e32 v118, vcc, 0x1b000, v86
	v_addc_co_u32_e32 v119, vcc, 0, v87, vcc
	v_mul_f32_e32 v120, v0, v222
	v_mul_f32_e32 v120, v69, v120
	v_cvt_pk_bf16_f32 v120, v120, s0
	global_store_short v[88:89], v120, off
	v_mul_f32_e32 v121, v16, v222
	v_mul_f32_e32 v121, v67, v121
	v_cvt_pk_bf16_f32 v121, v121, s0
	global_store_short v[88:89], v121, off offset:64
	v_mul_f32_e32 v122, v32, v222
	v_mul_f32_e32 v122, v68, v122
	v_cvt_pk_bf16_f32 v122, v122, s0
	global_store_short v[88:89], v122, off offset:128
	v_mul_f32_e32 v123, v48, v222
	v_mul_f32_e32 v123, v70, v123
	v_cvt_pk_bf16_f32 v123, v123, s0
	global_store_short v[88:89], v123, off offset:192
	v_mul_f32_e32 v124, v1, v223
	v_mul_f32_e32 v124, v69, v124
	v_cvt_pk_bf16_f32 v124, v124, s0
	global_store_short v[90:91], v124, off
	v_mul_f32_e32 v125, v17, v223
	v_mul_f32_e32 v125, v67, v125
	v_cvt_pk_bf16_f32 v125, v125, s0
	global_store_short v[90:91], v125, off offset:64
	v_mul_f32_e32 v126, v33, v223
	v_mul_f32_e32 v126, v68, v126
	v_cvt_pk_bf16_f32 v126, v126, s0
	global_store_short v[90:91], v126, off offset:128
	v_mul_f32_e32 v127, v49, v223
	v_mul_f32_e32 v127, v70, v127
	v_cvt_pk_bf16_f32 v127, v127, s0
	global_store_short v[90:91], v127, off offset:192
	v_mul_f32_e32 v120, v2, v224
	v_mul_f32_e32 v120, v69, v120
	v_cvt_pk_bf16_f32 v120, v120, s0
	global_store_short v[92:93], v120, off
	v_mul_f32_e32 v121, v18, v224
	v_mul_f32_e32 v121, v67, v121
	v_cvt_pk_bf16_f32 v121, v121, s0
	global_store_short v[92:93], v121, off offset:64
	v_mul_f32_e32 v122, v34, v224
	v_mul_f32_e32 v122, v68, v122
	v_cvt_pk_bf16_f32 v122, v122, s0
	global_store_short v[92:93], v122, off offset:128
	v_mul_f32_e32 v123, v50, v224
	v_mul_f32_e32 v123, v70, v123
	v_cvt_pk_bf16_f32 v123, v123, s0
	global_store_short v[92:93], v123, off offset:192
	v_mul_f32_e32 v124, v3, v225
	v_mul_f32_e32 v124, v69, v124
	v_cvt_pk_bf16_f32 v124, v124, s0
	global_store_short v[94:95], v124, off
	v_mul_f32_e32 v125, v19, v225
	v_mul_f32_e32 v125, v67, v125
	v_cvt_pk_bf16_f32 v125, v125, s0
	global_store_short v[94:95], v125, off offset:64
	v_mul_f32_e32 v126, v35, v225
	v_mul_f32_e32 v126, v68, v126
	v_cvt_pk_bf16_f32 v126, v126, s0
	global_store_short v[94:95], v126, off offset:128
	v_mul_f32_e32 v127, v51, v225
	v_mul_f32_e32 v127, v70, v127
	v_cvt_pk_bf16_f32 v127, v127, s0
	global_store_short v[94:95], v127, off offset:192
	v_mul_f32_e32 v120, v4, v226
	v_mul_f32_e32 v120, v69, v120
	v_cvt_pk_bf16_f32 v120, v120, s0
	global_store_short v[96:97], v120, off
	v_mul_f32_e32 v121, v20, v226
	v_mul_f32_e32 v121, v67, v121
	v_cvt_pk_bf16_f32 v121, v121, s0
	global_store_short v[96:97], v121, off offset:64
	v_mul_f32_e32 v122, v36, v226
	v_mul_f32_e32 v122, v68, v122
	v_cvt_pk_bf16_f32 v122, v122, s0
	global_store_short v[96:97], v122, off offset:128
	v_mul_f32_e32 v123, v52, v226
	v_mul_f32_e32 v123, v70, v123
	v_cvt_pk_bf16_f32 v123, v123, s0
	global_store_short v[96:97], v123, off offset:192
	v_mul_f32_e32 v124, v5, v227
	v_mul_f32_e32 v124, v69, v124
	v_cvt_pk_bf16_f32 v124, v124, s0
	global_store_short v[98:99], v124, off
	v_mul_f32_e32 v125, v21, v227
	v_mul_f32_e32 v125, v67, v125
	v_cvt_pk_bf16_f32 v125, v125, s0
; __device__ __forceinline__ int crow(int r, int hi) { return (r & 3) + 8 * (r >> 2) + 4 * hi; }
; template <bool FIXED> __device__ __forceinline__ void attn_unit(int b, int h, int qb, const bf16* __restrict__ P, bf16* __restrict__ MIX, const float* __restrict__ BT, const float* __restrict__ subg, ...
;     ...
;       for (int d0 = 0; d0 < 4; ++d0) Ow[(long)crow(r, hi) * DMODEL + d0 * 32] = __float2bfloat16(y[d0] * rs * gsub[d0]); }
	global_store_short v[98:99], v125, off offset:64
	v_mul_f32_e32 v126, v37, v227
	v_mul_f32_e32 v126, v68, v126
	v_cvt_pk_bf16_f32 v126, v126, s0
	global_store_short v[98:99], v126, off offset:128
	v_mul_f32_e32 v127, v53, v227
	v_mul_f32_e32 v127, v70, v127
	v_cvt_pk_bf16_f32 v127, v127, s0
	global_store_short v[98:99], v127, off offset:192
	v_mul_f32_e32 v120, v6, v228
	v_mul_f32_e32 v120, v69, v120
	v_cvt_pk_bf16_f32 v120, v120, s0
	global_store_short v[100:101], v120, off
	v_mul_f32_e32 v121, v22, v228
	v_mul_f32_e32 v121, v67, v121
	v_cvt_pk_bf16_f32 v121, v121, s0
	global_store_short v[100:101], v121, off offset:64
	v_mul_f32_e32 v122, v38, v228
	v_mul_f32_e32 v122, v68, v122
	v_cvt_pk_bf16_f32 v122, v122, s0
	global_store_short v[100:101], v122, off offset:128
	v_mul_f32_e32 v123, v54, v228
	v_mul_f32_e32 v123, v70, v123
	v_cvt_pk_bf16_f32 v123, v123, s0
	global_store_short v[100:101], v123, off offset:192
	v_mul_f32_e32 v124, v7, v229
	v_mul_f32_e32 v124, v69, v124
	v_cvt_pk_bf16_f32 v124, v124, s0
	global_store_short v[102:103], v124, off
	v_mul_f32_e32 v125, v23, v229
	v_mul_f32_e32 v125, v67, v125
	v_cvt_pk_bf16_f32 v125, v125, s0
	global_store_short v[102:103], v125, off offset:64
	v_mul_f32_e32 v126, v39, v229
	v_mul_f32_e32 v126, v68, v126
	v_cvt_pk_bf16_f32 v126, v126, s0
	global_store_short v[102:103], v126, off offset:128
	v_mul_f32_e32 v127, v55, v229
	v_mul_f32_e32 v127, v70, v127
	v_cvt_pk_bf16_f32 v127, v127, s0
	global_store_short v[102:103], v127, off offset:192
	v_mul_f32_e32 v120, v8, v230
	v_mul_f32_e32 v120, v69, v120
	v_cvt_pk_bf16_f32 v120, v120, s0
	global_store_short v[104:105], v120, off
	v_mul_f32_e32 v121, v24, v230
	v_mul_f32_e32 v121, v67, v121
	v_cvt_pk_bf16_f32 v121, v121, s0
	global_store_short v[104:105], v121, off offset:64
	v_mul_f32_e32 v122, v40, v230
	v_mul_f32_e32 v122, v68, v122
	v_cvt_pk_bf16_f32 v122, v122, s0
	global_store_short v[104:105], v122, off offset:128
	v_mul_f32_e32 v123, v56, v230
	v_mul_f32_e32 v123, v70, v123
	v_cvt_pk_bf16_f32 v123, v123, s0
	global_store_short v[104:105], v123, off offset:192
	v_mul_f32_e32 v124, v9, v231
	v_mul_f32_e32 v124, v69, v124
	v_cvt_pk_bf16_f32 v124, v124, s0
	global_store_short v[106:107], v124, off
	v_mul_f32_e32 v125, v25, v231
	v_mul_f32_e32 v125, v67, v125
	v_cvt_pk_bf16_f32 v125, v125, s0
	global_store_short v[106:107], v125, off offset:64
	v_mul_f32_e32 v126, v41, v231
	v_mul_f32_e32 v126, v68, v126
	v_cvt_pk_bf16_f32 v126, v126, s0
	global_store_short v[106:107], v126, off offset:128
	v_mul_f32_e32 v127, v57, v231
	v_mul_f32_e32 v127, v70, v127
	v_cvt_pk_bf16_f32 v127, v127, s0
	global_store_short v[106:107], v127, off offset:192
	v_mul_f32_e32 v120, v10, v232
	v_mul_f32_e32 v120, v69, v120
	v_cvt_pk_bf16_f32 v120, v120, s0
	global_store_short v[108:109], v120, off
	v_mul_f32_e32 v121, v26, v232
	v_mul_f32_e32 v121, v67, v121
	v_cvt_pk_bf16_f32 v121, v121, s0
	global_store_short v[108:109], v121, off offset:64
	v_mul_f32_e32 v122, v42, v232
	v_mul_f32_e32 v122, v68, v122
	v_cvt_pk_bf16_f32 v122, v122, s0
	global_store_short v[108:109], v122, off offset:128
	v_mul_f32_e32 v123, v58, v232
	v_mul_f32_e32 v123, v70, v123
	v_cvt_pk_bf16_f32 v123, v123, s0
	global_store_short v[108:109], v123, off offset:192
	v_mul_f32_e32 v124, v11, v233
	v_mul_f32_e32 v124, v69, v124
	v_cvt_pk_bf16_f32 v124, v124, s0
	global_store_short v[110:111], v124, off
	v_mul_f32_e32 v125, v27, v233
	v_mul_f32_e32 v125, v67, v125
	v_cvt_pk_bf16_f32 v125, v125, s0
	global_store_short v[110:111], v125, off offset:64
	v_mul_f32_e32 v126, v43, v233
	v_mul_f32_e32 v126, v68, v126
	v_cvt_pk_bf16_f32 v126, v126, s0
	global_store_short v[110:111], v126, off offset:128
	v_mul_f32_e32 v127, v59, v233
	v_mul_f32_e32 v127, v70, v127
	v_cvt_pk_bf16_f32 v127, v127, s0
	global_store_short v[110:111], v127, off offset:192
	v_mul_f32_e32 v120, v12, v234
	v_mul_f32_e32 v120, v69, v120
	v_cvt_pk_bf16_f32 v120, v120, s0
	global_store_short v[112:113], v120, off
	v_mul_f32_e32 v121, v28, v234
	v_mul_f32_e32 v121, v67, v121
	v_cvt_pk_bf16_f32 v121, v121, s0
	global_store_short v[112:113], v121, off offset:64
	v_mul_f32_e32 v122, v44, v234
	v_mul_f32_e32 v122, v68, v122
	v_cvt_pk_bf16_f32 v122, v122, s0
	global_store_short v[112:113], v122, off offset:128
	v_mul_f32_e32 v123, v60, v234
	v_mul_f32_e32 v123, v70, v123
	v_cvt_pk_bf16_f32 v123, v123, s0
	global_store_short v[112:113], v123, off offset:192
	v_mul_f32_e32 v124, v13, v235
	v_mul_f32_e32 v124, v69, v124
	v_cvt_pk_bf16_f32 v124, v124, s0
	global_store_short v[114:115], v124, off
	v_mul_f32_e32 v125, v29, v235
	v_mul_f32_e32 v125, v67, v125
	v_cvt_pk_bf16_f32 v125, v125, s0
	global_store_short v[114:115], v125, off offset:64
	v_mul_f32_e32 v126, v45, v235
	v_mul_f32_e32 v126, v68, v126
	v_cvt_pk_bf16_f32 v126, v126, s0
	global_store_short v[114:115], v126, off offset:128
	v_mul_f32_e32 v127, v61, v235
	v_mul_f32_e32 v127, v70, v127
	v_cvt_pk_bf16_f32 v127, v127, s0
	global_store_short v[114:115], v127, off offset:192
	v_mul_f32_e32 v120, v14, v236
	v_mul_f32_e32 v120, v69, v120
	v_cvt_pk_bf16_f32 v120, v120, s0
	global_store_short v[116:117], v120, off
	v_mul_f32_e32 v121, v30, v236
	v_mul_f32_e32 v121, v67, v121
	v_cvt_pk_bf16_f32 v121, v121, s0
	global_store_short v[116:117], v121, off offset:64
	v_mul_f32_e32 v122, v46, v236
	v_mul_f32_e32 v122, v68, v122
	v_cvt_pk_bf16_f32 v122, v122, s0
	global_store_short v[116:117], v122, off offset:128
	v_mul_f32_e32 v123, v62, v236
	v_mul_f32_e32 v123, v70, v123
	v_cvt_pk_bf16_f32 v123, v123, s0
	global_store_short v[116:117], v123, off offset:192
	v_mul_f32_e32 v124, v15, v237
	v_mul_f32_e32 v124, v69, v124
	v_cvt_pk_bf16_f32 v124, v124, s0
	global_store_short v[118:119], v124, off
	v_mul_f32_e32 v125, v31, v237
	v_mul_f32_e32 v125, v67, v125
	v_cvt_pk_bf16_f32 v125, v125, s0
	global_store_short v[118:119], v125, off offset:64
	v_mul_f32_e32 v126, v47, v237
	v_mul_f32_e32 v126, v68, v126
	v_cvt_pk_bf16_f32 v126, v126, s0
	global_store_short v[118:119], v126, off offset:128
	v_mul_f32_e32 v127, v63, v237
	v_mul_f32_e32 v127, v70, v127
	v_cvt_pk_bf16_f32 v127, v127, s0
	global_store_short v[118:119], v127, off offset:192
; __device__ __forceinline__ void conv_item(const bf16* __restrict__ P, bf16* __restrict__ MIX, const float* __restrict__ cw, int it, int lane) {
;     ...
;   for (int j = 0; j < 2; ++j) { const int c0 = j * 512 + lane * 8;
;     float w0[8], w1[8], w2[8];
; #pragma unroll
;     for (int e = 0; e < 8; ++e) { w0[e] = cw[c0 + e]; w1[e] = cw[1024 + c0 + e]; w2[e] = cw[2048 + c0 + e]; }
;     float p[6][8];
; #pragma unroll
;     for (int k = 0; k < 6; ++k) { const int t = t0 - 2 + k;
;       if (k < 2 && first) {
; #pragma unroll
;         for (int e = 0; e < 8; ++e) p[k][e] = 0.f;
;       } else { const u32x4 gp = *(const u32x4*)(Pu + (size_t)t * PW + 4096 + c0);
; #pragma unroll
;         for (int e = 0; e < 4; ++e) { p[k][2 * e] = __uint_as_float(gp[e] << 16); p[k][2 * e + 1] = __uint_as_float(gp[e] & 0xffff0000u); } } }
; #pragma unroll
;     for (int i = 0; i < 4; ++i) { const u32x4 gb = *(const u32x4*)(Pu + (size_t)(t0 + i) * PW + 3072 + c0); float r[8];
; #pragma unroll
;       for (int e = 0; e < 4; ++e) { r[2 * e] = __uint_as_float(gb[e] << 16) * (w0[2 * e] * p[i][2 * e] + w1[2 * e] * p[i + 1][2 * e] + w2[2 * e] * p[i + 2][2 * e]);
;         r[2 * e + 1] = __uint_as_float(gb[e] & 0xffff0000u) * (w0[2 * e + 1] * p[i][2 * e + 1] + w1[2 * e + 1] * p[i + 1][2 * e + 1] + w2[2 * e + 1] * p[i + 2][2 * e + 1]); }
.LBB0_330:
	s_andn2_b64 vcc, exec, s[84:85]
	s_cbranch_vccnz .LBB0_340
	s_or_b32 s0, s24, s71
	s_lshl_b32 s80, s0, 2
	s_and_b32 s6, s0, 0x1ff
	s_cmp_eq_u32 s6, 0
	s_cselect_b32 s59, 0, -1
	s_add_i32 s60, s80, -2
	s_mul_hi_i32 s56, s60, 0x3000
	s_mulk_i32 s60, 0x3000
	s_add_u32 s22, s14, s60
	s_addc_u32 s23, s46, s56
	s_add_u32 s22, s22, 0x2000
	s_addc_u32 s23, s23, 0
	s_add_u32 s28, s22, 0x5800
	s_addc_u32 s29, s23, 0
	s_ashr_i32 s81, s80, 31
	s_lshl_b64 s[0:1], s[80:81], 12
	s_add_u32 s0, s42, s0
	s_addc_u32 s1, s43, s1
	v_lshlrev_b32_e32 v204, 2, v166
	v_lshlrev_b32_e32 v198, 1, v166
	v_add_u32_e32 v205, 0x1000, v204
	v_add_u32_e32 v206, 0x2000, v204
	v_add_u32_e32 v199, 0x3000, v198
	v_add_u32_e32 v200, 0x6000, v198
	v_add_u32_e32 v201, 0x9000, v198
	v_add_u32_e32 v202, 0xc000, v198
	v_add_u32_e32 v203, 0xf000, v198
	v_add_u32_e32 v207, 0x1000, v198
	v_add_u32_e32 v208, 0x2000, v198
	global_load_dwordx4 v[0:3], v204, s[52:53]
	global_load_dwordx4 v[4:7], v204, s[52:53] offset:16
	global_load_dwordx4 v[8:11], v205, s[52:53]
	global_load_dwordx4 v[12:15], v205, s[52:53] offset:16
	global_load_dwordx4 v[16:19], v206, s[52:53]
	global_load_dwordx4 v[20:23], v206, s[52:53] offset:16
	global_load_dwordx4 v[48:51], v198, s[22:23]
	global_load_dwordx4 v[52:55], v199, s[22:23]
	global_load_dwordx4 v[56:59], v200, s[22:23]
	global_load_dwordx4 v[60:63], v201, s[22:23]
	global_load_dwordx4 v[64:67], v202, s[22:23]
	global_load_dwordx4 v[68:71], v203, s[22:23]
	global_load_dwordx4 v[96:99], v198, s[28:29]
	global_load_dwordx4 v[100:103], v199, s[28:29]
	global_load_dwordx4 v[104:107], v200, s[28:29]
	global_load_dwordx4 v[108:111], v201, s[28:29]
	global_load_dwordx4 v[24:27], v204, s[52:53] offset:2048
	global_load_dwordx4 v[28:31], v204, s[52:53] offset:2064
	global_load_dwordx4 v[32:35], v205, s[52:53] offset:2048
	global_load_dwordx4 v[36:39], v205, s[52:53] offset:2064
	global_load_dwordx4 v[40:43], v206, s[52:53] offset:2048
	global_load_dwordx4 v[44:47], v206, s[52:53] offset:2064
	global_load_dwordx4 v[72:75], v198, s[22:23] offset:1024
	global_load_dwordx4 v[76:79], v199, s[22:23] offset:1024
	global_load_dwordx4 v[80:83], v200, s[22:23] offset:1024
	global_load_dwordx4 v[84:87], v201, s[22:23] offset:1024
	global_load_dwordx4 v[88:91], v202, s[22:23] offset:1024
	global_load_dwordx4 v[92:95], v203, s[22:23] offset:1024
	global_load_dwordx4 v[112:115], v198, s[28:29] offset:1024
	global_load_dwordx4 v[116:119], v199, s[28:29] offset:1024
	global_load_dwordx4 v[120:123], v200, s[28:29] offset:1024
	global_load_dwordx4 v[124:127], v201, s[28:29] offset:1024
	s_and_b64 vcc, exec, s[30:31]
	s_cbranch_vccz .Lmy_nopf_b
	s_add_u32 s98, s92, 0x1a200800
	s_addc_u32 s99, s93, 0
	s_sub_u32 s100, s92, 0x180000
	s_subb_u32 s101, s93, 0
	s_add_u32 s100, s100, s4
	s_addc_u32 s101, s101, s5
	s_add_i32 m0, s27, 0x10000
	s_nop 0
	global_load_lds_dwordx4 v140, s[98:99]
	s_add_i32 m0, s27, 0x14000
	s_nop 0
	global_load_lds_dwordx4 v136, s[100:101]
	s_add_i32 m0, s27, 0x10400
	s_sub_u32 s100, s92, 0x180000
	s_subb_u32 s101, s93, 0
	s_add_u32 s100, s100, s74
	s_addc_u32 s101, s101, s75
	global_load_lds_dwordx4 v138, s[98:99]
	s_add_i32 m0, s27, 0x14400
	s_nop 0
	global_load_lds_dwordx4 v136, s[100:101]
.Lmy_nopf_b:
	s_and_b64 vcc, exec, s[30:31]
	s_cbranch_vccz .Lmy_w0_b
	s_waitcnt vmcnt(20)
	s_branch .Lmy_w1_b
.Lmy_w0_b:
	s_waitcnt vmcnt(16)
.Lmy_w1_b:
	v_and_b32_e32 v48, s59, v48
	v_and_b32_e32 v49, s59, v49
	v_and_b32_e32 v50, s59, v50
	v_and_b32_e32 v51, s59, v51
	v_and_b32_e32 v52, s59, v52
	v_and_b32_e32 v53, s59, v53
	v_and_b32_e32 v54, s59, v54
	v_and_b32_e32 v55, s59, v55
	v_lshlrev_b32_e32 v212, 16, v48
	v_and_b32_e32 v213, 0xffff0000, v48
	v_lshlrev_b32_e32 v214, 16, v52
	v_and_b32_e32 v215, 0xffff0000, v52
	v_lshlrev_b32_e32 v216, 16, v56
	v_and_b32_e32 v217, 0xffff0000, v56
	v_lshlrev_b32_e32 v218, 16, v60
	v_and_b32_e32 v219, 0xffff0000, v60
	v_lshlrev_b32_e32 v220, 16, v64
	v_and_b32_e32 v221, 0xffff0000, v64
	v_lshlrev_b32_e32 v222, 16, v68
	v_and_b32_e32 v223, 0xffff0000, v68
	v_lshlrev_b32_e32 v224, 16, v96
	v_and_b32_e32 v225, 0xffff0000, v96
	v_lshlrev_b32_e32 v226, 16, v100
	v_and_b32_e32 v227, 0xffff0000, v100
	v_lshlrev_b32_e32 v228, 16, v104
	v_and_b32_e32 v229, 0xffff0000, v104
	v_lshlrev_b32_e32 v230, 16, v108
	v_and_b32_e32 v231, 0xffff0000, v108
	v_pk_mul_f32 v[232:233], v[0:1], v[212:213]
	v_pk_mul_f32 v[234:235], v[0:1], v[214:215]
	v_pk_mul_f32 v[236:237], v[0:1], v[216:217]
	v_pk_mul_f32 v[238:239], v[0:1], v[218:219]
	v_pk_fma_f32 v[232:233], v[8:9], v[214:215], v[232:233]
	v_pk_fma_f32 v[234:235], v[8:9], v[216:217], v[234:235]
	v_pk_fma_f32 v[236:237], v[8:9], v[218:219], v[236:237]
	v_pk_fma_f32 v[238:239], v[8:9], v[220:221], v[238:239]
	v_pk_fma_f32 v[232:233], v[16:17], v[216:217], v[232:233]
	v_pk_fma_f32 v[234:235], v[16:17], v[218:219], v[234:235]
	v_pk_fma_f32 v[236:237], v[16:17], v[220:221], v[236:237]
	v_pk_fma_f32 v[238:239], v[16:17], v[222:223], v[238:239]
	v_pk_mul_f32 v[232:233], v[224:225], v[232:233]
	v_pk_mul_f32 v[234:235], v[226:227], v[234:235]
	v_pk_mul_f32 v[236:237], v[228:229], v[236:237]
	v_pk_mul_f32 v[238:239], v[230:231], v[238:239]
	v_cvt_pk_bf16_f32 v96, v232, v233
	v_cvt_pk_bf16_f32 v100, v234, v235
; __device__ __forceinline__ unsigned cvtpk(float lo, float hi) { unsigned r; asm volatile("v_cvt_pk_bf16_f32 %0, %1, %2" : "=v"(r) : "v"(lo), "v"(hi)); return r; }
; __device__ __forceinline__ void conv_item(const bf16* __restrict__ P, bf16* __restrict__ MIX, const float* __restrict__ cw, int it, int lane) {
;     ...
;     for (int i = 0; i < 4; ++i) { const u32x4 gb = *(const u32x4*)(Pu + (size_t)(t0 + i) * PW + 3072 + c0); float r[8];
; #pragma unroll
;       for (int e = 0; e < 4; ++e) { r[2 * e] = __uint_as_float(gb[e] << 16) * (w0[2 * e] * p[i][2 * e] + w1[2 * e] * p[i + 1][2 * e] + w2[2 * e] * p[i + 2][2 * e]);
;         r[2 * e + 1] = __uint_as_float(gb[e] & 0xffff0000u) * (w0[2 * e + 1] * p[i][2 * e + 1] + w1[2 * e + 1] * p[i + 1][2 * e + 1] + w2[2 * e + 1] * p[i + 2][2 * e + 1]); }
;       u32x4 o; o.x = cvtpk(r[0], r[1]); o.y = cvtpk(r[2], r[3]); o.z = cvtpk(r[4], r[5]); o.w = cvtpk(r[6], r[7]);
;       *(u32x4*)(Mu + (size_t)(t0 + i) * DMODEL + 1024 + c0) = o; } }
	v_cvt_pk_bf16_f32 v104, v236, v237
	v_cvt_pk_bf16_f32 v108, v238, v239
	v_lshlrev_b32_e32 v212, 16, v49
	v_and_b32_e32 v213, 0xffff0000, v49
	v_lshlrev_b32_e32 v214, 16, v53
	v_and_b32_e32 v215, 0xffff0000, v53
	v_lshlrev_b32_e32 v216, 16, v57
	v_and_b32_e32 v217, 0xffff0000, v57
	v_lshlrev_b32_e32 v218, 16, v61
	v_and_b32_e32 v219, 0xffff0000, v61
	v_lshlrev_b32_e32 v220, 16, v65
	v_and_b32_e32 v221, 0xffff0000, v65
	v_lshlrev_b32_e32 v222, 16, v69
	v_and_b32_e32 v223, 0xffff0000, v69
	v_lshlrev_b32_e32 v224, 16, v97
	v_and_b32_e32 v225, 0xffff0000, v97
	v_lshlrev_b32_e32 v226, 16, v101
	v_and_b32_e32 v227, 0xffff0000, v101
	v_lshlrev_b32_e32 v228, 16, v105
	v_and_b32_e32 v229, 0xffff0000, v105
	v_lshlrev_b32_e32 v230, 16, v109
	v_and_b32_e32 v231, 0xffff0000, v109
	v_pk_mul_f32 v[232:233], v[2:3], v[212:213]
	v_pk_mul_f32 v[234:235], v[2:3], v[214:215]
	v_pk_mul_f32 v[236:237], v[2:3], v[216:217]
	v_pk_mul_f32 v[238:239], v[2:3], v[218:219]
	v_pk_fma_f32 v[232:233], v[10:11], v[214:215], v[232:233]
	v_pk_fma_f32 v[234:235], v[10:11], v[216:217], v[234:235]
	v_pk_fma_f32 v[236:237], v[10:11], v[218:219], v[236:237]
	v_pk_fma_f32 v[238:239], v[10:11], v[220:221], v[238:239]
	v_pk_fma_f32 v[232:233], v[18:19], v[216:217], v[232:233]
	v_pk_fma_f32 v[234:235], v[18:19], v[218:219], v[234:235]
	v_pk_fma_f32 v[236:237], v[18:19], v[220:221], v[236:237]
	v_pk_fma_f32 v[238:239], v[18:19], v[222:223], v[238:239]
	v_pk_mul_f32 v[232:233], v[224:225], v[232:233]
	v_pk_mul_f32 v[234:235], v[226:227], v[234:235]
	v_pk_mul_f32 v[236:237], v[228:229], v[236:237]
	v_pk_mul_f32 v[238:239], v[230:231], v[238:239]
	v_cvt_pk_bf16_f32 v97, v232, v233
	v_cvt_pk_bf16_f32 v101, v234, v235
	v_cvt_pk_bf16_f32 v105, v236, v237
	v_cvt_pk_bf16_f32 v109, v238, v239
	v_lshlrev_b32_e32 v212, 16, v50
	v_and_b32_e32 v213, 0xffff0000, v50
	v_lshlrev_b32_e32 v214, 16, v54
	v_and_b32_e32 v215, 0xffff0000, v54
	v_lshlrev_b32_e32 v216, 16, v58
	v_and_b32_e32 v217, 0xffff0000, v58
	v_lshlrev_b32_e32 v218, 16, v62
	v_and_b32_e32 v219, 0xffff0000, v62
	v_lshlrev_b32_e32 v220, 16, v66
	v_and_b32_e32 v221, 0xffff0000, v66
	v_lshlrev_b32_e32 v222, 16, v70
	v_and_b32_e32 v223, 0xffff0000, v70
	v_lshlrev_b32_e32 v224, 16, v98
	v_and_b32_e32 v225, 0xffff0000, v98
	v_lshlrev_b32_e32 v226, 16, v102
	v_and_b32_e32 v227, 0xffff0000, v102
	v_lshlrev_b32_e32 v228, 16, v106
	v_and_b32_e32 v229, 0xffff0000, v106
	v_lshlrev_b32_e32 v230, 16, v110
	v_and_b32_e32 v231, 0xffff0000, v110
	v_pk_mul_f32 v[232:233], v[4:5], v[212:213]
	v_pk_mul_f32 v[234:235], v[4:5], v[214:215]
	v_pk_mul_f32 v[236:237], v[4:5], v[216:217]
	v_pk_mul_f32 v[238:239], v[4:5], v[218:219]
	v_pk_fma_f32 v[232:233], v[12:13], v[214:215], v[232:233]
	v_pk_fma_f32 v[234:235], v[12:13], v[216:217], v[234:235]
	v_pk_fma_f32 v[236:237], v[12:13], v[218:219], v[236:237]
	v_pk_fma_f32 v[238:239], v[12:13], v[220:221], v[238:239]
	v_pk_fma_f32 v[232:233], v[20:21], v[216:217], v[232:233]
	v_pk_fma_f32 v[234:235], v[20:21], v[218:219], v[234:235]
	v_pk_fma_f32 v[236:237], v[20:21], v[220:221], v[236:237]
	v_pk_fma_f32 v[238:239], v[20:21], v[222:223], v[238:239]
	v_pk_mul_f32 v[232:233], v[224:225], v[232:233]
	v_pk_mul_f32 v[234:235], v[226:227], v[234:235]
	v_pk_mul_f32 v[236:237], v[228:229], v[236:237]
	v_pk_mul_f32 v[238:239], v[230:231], v[238:239]
	v_cvt_pk_bf16_f32 v98, v232, v233
	v_cvt_pk_bf16_f32 v102, v234, v235
	v_cvt_pk_bf16_f32 v106, v236, v237
	v_cvt_pk_bf16_f32 v110, v238, v239
	v_lshlrev_b32_e32 v212, 16, v51
	v_and_b32_e32 v213, 0xffff0000, v51
	v_lshlrev_b32_e32 v214, 16, v55
	v_and_b32_e32 v215, 0xffff0000, v55
	v_lshlrev_b32_e32 v216, 16, v59
	v_and_b32_e32 v217, 0xffff0000, v59
	v_lshlrev_b32_e32 v218, 16, v63
	v_and_b32_e32 v219, 0xffff0000, v63
	v_lshlrev_b32_e32 v220, 16, v67
	v_and_b32_e32 v221, 0xffff0000, v67
	v_lshlrev_b32_e32 v222, 16, v71
	v_and_b32_e32 v223, 0xffff0000, v71
	v_lshlrev_b32_e32 v224, 16, v99
	v_and_b32_e32 v225, 0xffff0000, v99
	v_lshlrev_b32_e32 v226, 16, v103
	v_and_b32_e32 v227, 0xffff0000, v103
	v_lshlrev_b32_e32 v228, 16, v107
	v_and_b32_e32 v229, 0xffff0000, v107
	v_lshlrev_b32_e32 v230, 16, v111
	v_and_b32_e32 v231, 0xffff0000, v111
	v_pk_mul_f32 v[232:233], v[6:7], v[212:213]
	v_pk_mul_f32 v[234:235], v[6:7], v[214:215]
	v_pk_mul_f32 v[236:237], v[6:7], v[216:217]
	v_pk_mul_f32 v[238:239], v[6:7], v[218:219]
	v_pk_fma_f32 v[232:233], v[14:15], v[214:215], v[232:233]
	v_pk_fma_f32 v[234:235], v[14:15], v[216:217], v[234:235]
	v_pk_fma_f32 v[236:237], v[14:15], v[218:219], v[236:237]
	v_pk_fma_f32 v[238:239], v[14:15], v[220:221], v[238:239]
	v_pk_fma_f32 v[232:233], v[22:23], v[216:217], v[232:233]
	v_pk_fma_f32 v[234:235], v[22:23], v[218:219], v[234:235]
	v_pk_fma_f32 v[236:237], v[22:23], v[220:221], v[236:237]
	v_pk_fma_f32 v[238:239], v[22:23], v[222:223], v[238:239]
	v_pk_mul_f32 v[232:233], v[224:225], v[232:233]
	v_pk_mul_f32 v[234:235], v[226:227], v[234:235]
	v_pk_mul_f32 v[236:237], v[228:229], v[236:237]
	v_pk_mul_f32 v[238:239], v[230:231], v[238:239]
	v_cvt_pk_bf16_f32 v99, v232, v233
	v_cvt_pk_bf16_f32 v103, v234, v235
	v_cvt_pk_bf16_f32 v107, v236, v237
	v_cvt_pk_bf16_f32 v111, v238, v239
	s_and_b64 vcc, exec, s[30:31]
	s_cbranch_vccz .Lmy_w0_c
	s_waitcnt vmcnt(4)
	s_branch .Lmy_w1_c

; __device__ __forceinline__ unsigned cvtpk(float lo, float hi) { unsigned r; asm volatile("v_cvt_pk_bf16_f32 %0, %1, %2" : "=v"(r) : "v"(lo), "v"(hi)); return r; }
; __device__ __forceinline__ void conv_item(const bf16* __restrict__ P, bf16* __restrict__ MIX, const float* __restrict__ cw, int it, int lane) {
;     ...
;     for (int i = 0; i < 4; ++i) { const u32x4 gb = *(const u32x4*)(Pu + (size_t)(t0 + i) * PW + 3072 + c0); float r[8];
; #pragma unroll
;       for (int e = 0; e < 4; ++e) { r[2 * e] = __uint_as_float(gb[e] << 16) * (w0[2 * e] * p[i][2 * e] + w1[2 * e] * p[i + 1][2 * e] + w2[2 * e] * p[i + 2][2 * e]);
;         r[2 * e + 1] = __uint_as_float(gb[e] & 0xffff0000u) * (w0[2 * e + 1] * p[i][2 * e + 1] + w1[2 * e + 1] * p[i + 1][2 * e + 1] + w2[2 * e + 1] * p[i + 2][2 * e + 1]); }
;       u32x4 o; o.x = cvtpk(r[0], r[1]); o.y = cvtpk(r[2], r[3]); o.z = cvtpk(r[4], r[5]); o.w = cvtpk(r[6], r[7]);
.Lmy_w1_c:
	v_and_b32_e32 v72, s59, v72
	v_and_b32_e32 v73, s59, v73
	v_and_b32_e32 v74, s59, v74
	v_and_b32_e32 v75, s59, v75
	v_and_b32_e32 v76, s59, v76
	v_and_b32_e32 v77, s59, v77
	v_and_b32_e32 v78, s59, v78
	v_and_b32_e32 v79, s59, v79
	v_lshlrev_b32_e32 v212, 16, v72
	v_and_b32_e32 v213, 0xffff0000, v72
	v_lshlrev_b32_e32 v214, 16, v76
	v_and_b32_e32 v215, 0xffff0000, v76
	v_lshlrev_b32_e32 v216, 16, v80
	v_and_b32_e32 v217, 0xffff0000, v80
	v_lshlrev_b32_e32 v218, 16, v84
	v_and_b32_e32 v219, 0xffff0000, v84
	v_lshlrev_b32_e32 v220, 16, v88
	v_and_b32_e32 v221, 0xffff0000, v88
	v_lshlrev_b32_e32 v222, 16, v92
	v_and_b32_e32 v223, 0xffff0000, v92
	v_lshlrev_b32_e32 v224, 16, v112
	v_and_b32_e32 v225, 0xffff0000, v112
	v_lshlrev_b32_e32 v226, 16, v116
	v_and_b32_e32 v227, 0xffff0000, v116
	v_lshlrev_b32_e32 v228, 16, v120
	v_and_b32_e32 v229, 0xffff0000, v120
	v_lshlrev_b32_e32 v230, 16, v124
	v_and_b32_e32 v231, 0xffff0000, v124
	v_pk_mul_f32 v[232:233], v[24:25], v[212:213]
	v_pk_mul_f32 v[234:235], v[24:25], v[214:215]
	v_pk_mul_f32 v[236:237], v[24:25], v[216:217]
	v_pk_mul_f32 v[238:239], v[24:25], v[218:219]
	v_pk_fma_f32 v[232:233], v[32:33], v[214:215], v[232:233]
	v_pk_fma_f32 v[234:235], v[32:33], v[216:217], v[234:235]
	v_pk_fma_f32 v[236:237], v[32:33], v[218:219], v[236:237]
	v_pk_fma_f32 v[238:239], v[32:33], v[220:221], v[238:239]
	v_pk_fma_f32 v[232:233], v[40:41], v[216:217], v[232:233]
	v_pk_fma_f32 v[234:235], v[40:41], v[218:219], v[234:235]
	v_pk_fma_f32 v[236:237], v[40:41], v[220:221], v[236:237]
	v_pk_fma_f32 v[238:239], v[40:41], v[222:223], v[238:239]
	v_pk_mul_f32 v[232:233], v[224:225], v[232:233]
	v_pk_mul_f32 v[234:235], v[226:227], v[234:235]
	v_pk_mul_f32 v[236:237], v[228:229], v[236:237]
	v_pk_mul_f32 v[238:239], v[230:231], v[238:239]
	v_cvt_pk_bf16_f32 v112, v232, v233
	v_cvt_pk_bf16_f32 v116, v234, v235
	v_cvt_pk_bf16_f32 v120, v236, v237
	v_cvt_pk_bf16_f32 v124, v238, v239
	v_lshlrev_b32_e32 v212, 16, v73
	v_and_b32_e32 v213, 0xffff0000, v73
	v_lshlrev_b32_e32 v214, 16, v77
	v_and_b32_e32 v215, 0xffff0000, v77
	v_lshlrev_b32_e32 v216, 16, v81
	v_and_b32_e32 v217, 0xffff0000, v81
	v_lshlrev_b32_e32 v218, 16, v85
	v_and_b32_e32 v219, 0xffff0000, v85
	v_lshlrev_b32_e32 v220, 16, v89
	v_and_b32_e32 v221, 0xffff0000, v89
	v_lshlrev_b32_e32 v222, 16, v93
	v_and_b32_e32 v223, 0xffff0000, v93
	v_lshlrev_b32_e32 v224, 16, v113
	v_and_b32_e32 v225, 0xffff0000, v113
	v_lshlrev_b32_e32 v226, 16, v117
	v_and_b32_e32 v227, 0xffff0000, v117
	v_lshlrev_b32_e32 v228, 16, v121
	v_and_b32_e32 v229, 0xffff0000, v121
	v_lshlrev_b32_e32 v230, 16, v125
	v_and_b32_e32 v231, 0xffff0000, v125
	v_pk_mul_f32 v[232:233], v[26:27], v[212:213]
	v_pk_mul_f32 v[234:235], v[26:27], v[214:215]
	v_pk_mul_f32 v[236:237], v[26:27], v[216:217]
	v_pk_mul_f32 v[238:239], v[26:27], v[218:219]
	v_pk_fma_f32 v[232:233], v[34:35], v[214:215], v[232:233]
	v_pk_fma_f32 v[234:235], v[34:35], v[216:217], v[234:235]
	v_pk_fma_f32 v[236:237], v[34:35], v[218:219], v[236:237]
	v_pk_fma_f32 v[238:239], v[34:35], v[220:221], v[238:239]
	v_pk_fma_f32 v[232:233], v[42:43], v[216:217], v[232:233]
	v_pk_fma_f32 v[234:235], v[42:43], v[218:219], v[234:235]
	v_pk_fma_f32 v[236:237], v[42:43], v[220:221], v[236:237]
	v_pk_fma_f32 v[238:239], v[42:43], v[222:223], v[238:239]
	v_pk_mul_f32 v[232:233], v[224:225], v[232:233]
	v_pk_mul_f32 v[234:235], v[226:227], v[234:235]
	v_pk_mul_f32 v[236:237], v[228:229], v[236:237]
	v_pk_mul_f32 v[238:239], v[230:231], v[238:239]
	v_cvt_pk_bf16_f32 v113, v232, v233
	v_cvt_pk_bf16_f32 v117, v234, v235
	v_cvt_pk_bf16_f32 v121, v236, v237
	v_cvt_pk_bf16_f32 v125, v238, v239
	v_lshlrev_b32_e32 v212, 16, v74
	v_and_b32_e32 v213, 0xffff0000, v74
	v_lshlrev_b32_e32 v214, 16, v78
; __device__ __forceinline__ unsigned cvtpk(float lo, float hi) { unsigned r; asm volatile("v_cvt_pk_bf16_f32 %0, %1, %2" : "=v"(r) : "v"(lo), "v"(hi)); return r; }
; __device__ __forceinline__ void conv_item(const bf16* __restrict__ P, bf16* __restrict__ MIX, const float* __restrict__ cw, int it, int lane) {
;     ...
;     for (int i = 0; i < 4; ++i) { const u32x4 gb = *(const u32x4*)(Pu + (size_t)(t0 + i) * PW + 3072 + c0); float r[8];
; #pragma unroll
;       for (int e = 0; e < 4; ++e) { r[2 * e] = __uint_as_float(gb[e] << 16) * (w0[2 * e] * p[i][2 * e] + w1[2 * e] * p[i + 1][2 * e] + w2[2 * e] * p[i + 2][2 * e]);
;         r[2 * e + 1] = __uint_as_float(gb[e] & 0xffff0000u) * (w0[2 * e + 1] * p[i][2 * e + 1] + w1[2 * e + 1] * p[i + 1][2 * e + 1] + w2[2 * e + 1] * p[i + 2][2 * e + 1]); }
;       u32x4 o; o.x = cvtpk(r[0], r[1]); o.y = cvtpk(r[2], r[3]); o.z = cvtpk(r[4], r[5]); o.w = cvtpk(r[6], r[7]);
;       *(u32x4*)(Mu + (size_t)(t0 + i) * DMODEL + 1024 + c0) = o; } }
	v_and_b32_e32 v215, 0xffff0000, v78
	v_lshlrev_b32_e32 v216, 16, v82
	v_and_b32_e32 v217, 0xffff0000, v82
	v_lshlrev_b32_e32 v218, 16, v86
	v_and_b32_e32 v219, 0xffff0000, v86
	v_lshlrev_b32_e32 v220, 16, v90
	v_and_b32_e32 v221, 0xffff0000, v90
	v_lshlrev_b32_e32 v222, 16, v94
	v_and_b32_e32 v223, 0xffff0000, v94
	v_lshlrev_b32_e32 v224, 16, v114
	v_and_b32_e32 v225, 0xffff0000, v114
	v_lshlrev_b32_e32 v226, 16, v118
	v_and_b32_e32 v227, 0xffff0000, v118
	v_lshlrev_b32_e32 v228, 16, v122
	v_and_b32_e32 v229, 0xffff0000, v122
	v_lshlrev_b32_e32 v230, 16, v126
	v_and_b32_e32 v231, 0xffff0000, v126
	v_pk_mul_f32 v[232:233], v[28:29], v[212:213]
	v_pk_mul_f32 v[234:235], v[28:29], v[214:215]
	v_pk_mul_f32 v[236:237], v[28:29], v[216:217]
	v_pk_mul_f32 v[238:239], v[28:29], v[218:219]
	v_pk_fma_f32 v[232:233], v[36:37], v[214:215], v[232:233]
	v_pk_fma_f32 v[234:235], v[36:37], v[216:217], v[234:235]
	v_pk_fma_f32 v[236:237], v[36:37], v[218:219], v[236:237]
	v_pk_fma_f32 v[238:239], v[36:37], v[220:221], v[238:239]
	v_pk_fma_f32 v[232:233], v[44:45], v[216:217], v[232:233]
	v_pk_fma_f32 v[234:235], v[44:45], v[218:219], v[234:235]
	v_pk_fma_f32 v[236:237], v[44:45], v[220:221], v[236:237]
	v_pk_fma_f32 v[238:239], v[44:45], v[222:223], v[238:239]
	v_pk_mul_f32 v[232:233], v[224:225], v[232:233]
	v_pk_mul_f32 v[234:235], v[226:227], v[234:235]
	v_pk_mul_f32 v[236:237], v[228:229], v[236:237]
	v_pk_mul_f32 v[238:239], v[230:231], v[238:239]
	v_cvt_pk_bf16_f32 v114, v232, v233
	v_cvt_pk_bf16_f32 v118, v234, v235
	v_cvt_pk_bf16_f32 v122, v236, v237
	v_cvt_pk_bf16_f32 v126, v238, v239
	v_lshlrev_b32_e32 v212, 16, v75
	v_and_b32_e32 v213, 0xffff0000, v75
	v_lshlrev_b32_e32 v214, 16, v79
	v_and_b32_e32 v215, 0xffff0000, v79
	v_lshlrev_b32_e32 v216, 16, v83
	v_and_b32_e32 v217, 0xffff0000, v83
	v_lshlrev_b32_e32 v218, 16, v87
	v_and_b32_e32 v219, 0xffff0000, v87
	v_lshlrev_b32_e32 v220, 16, v91
	v_and_b32_e32 v221, 0xffff0000, v91
	v_lshlrev_b32_e32 v222, 16, v95
	v_and_b32_e32 v223, 0xffff0000, v95
	v_lshlrev_b32_e32 v224, 16, v115
	v_and_b32_e32 v225, 0xffff0000, v115
	v_lshlrev_b32_e32 v226, 16, v119
	v_and_b32_e32 v227, 0xffff0000, v119
	v_lshlrev_b32_e32 v228, 16, v123
	v_and_b32_e32 v229, 0xffff0000, v123
	v_lshlrev_b32_e32 v230, 16, v127
	v_and_b32_e32 v231, 0xffff0000, v127
	v_pk_mul_f32 v[232:233], v[30:31], v[212:213]
	v_pk_mul_f32 v[234:235], v[30:31], v[214:215]
	v_pk_mul_f32 v[236:237], v[30:31], v[216:217]
	v_pk_mul_f32 v[238:239], v[30:31], v[218:219]
	v_pk_fma_f32 v[232:233], v[38:39], v[214:215], v[232:233]
	v_pk_fma_f32 v[234:235], v[38:39], v[216:217], v[234:235]
	v_pk_fma_f32 v[236:237], v[38:39], v[218:219], v[236:237]
	v_pk_fma_f32 v[238:239], v[38:39], v[220:221], v[238:239]
	v_pk_fma_f32 v[232:233], v[46:47], v[216:217], v[232:233]
	v_pk_fma_f32 v[234:235], v[46:47], v[218:219], v[234:235]
	v_pk_fma_f32 v[236:237], v[46:47], v[220:221], v[236:237]
	v_pk_fma_f32 v[238:239], v[46:47], v[222:223], v[238:239]
	v_pk_mul_f32 v[232:233], v[224:225], v[232:233]
	v_pk_mul_f32 v[234:235], v[226:227], v[234:235]
	v_pk_mul_f32 v[236:237], v[228:229], v[236:237]
	v_pk_mul_f32 v[238:239], v[230:231], v[238:239]
	v_cvt_pk_bf16_f32 v115, v232, v233
	v_cvt_pk_bf16_f32 v119, v234, v235
	v_cvt_pk_bf16_f32 v123, v236, v237
	v_cvt_pk_bf16_f32 v127, v238, v239
	global_store_dwordx4 v198, v[96:99], s[0:1] offset:2048
	global_store_dwordx4 v207, v[100:103], s[0:1] offset:2048
	global_store_dwordx4 v208, v[104:107], s[0:1] offset:2048
	global_store_dwordx4 v199, v[108:111], s[0:1] offset:2048
	global_store_dwordx4 v198, v[112:115], s[0:1] offset:3072
	global_store_dwordx4 v207, v[116:119], s[0:1] offset:3072
	global_store_dwordx4 v208, v[120:123], s[0:1] offset:3072
	global_store_dwordx4 v199, v[124:127], s[0:1] offset:3072
